# P0 weight transposes: all 32 loads of an item in flight (were 4 fully-drained batches of 8), counted waits before the LDS writes
# speedup vs baseline: 1.0172x; 1.0044x over previous
; #define LDS_WAIT() asm volatile("s_waitcnt lgkmcnt(0)" ::: "memory")
;     ...
; #pragma unroll 8
;     for (int i = 0; i < 32; ++i) { const int kk = 2 * i + (lane >> 5); scr[kk * 33 + (lane & 31)] = __builtin_nontemporal_load(W + (size_t)(k0 + kk) * N + n0 + (lane & 31)); }
;     LDS_WAIT(); asm volatile("" ::: "memory");
.LBB9_40:
	v_lshl_add_u64 v[72:73], v[52:53], 0, s[2:3]
	v_lshl_add_u64 v[74:75], v[50:51], 0, s[2:3]
	v_lshl_add_u64 v[76:77], v[48:49], 0, s[2:3]
	v_lshl_add_u64 v[78:79], v[46:47], 0, s[2:3]
	v_lshl_add_u64 v[80:81], v[44:45], 0, s[2:3]
	v_lshl_add_u64 v[82:83], v[42:43], 0, s[2:3]
	v_lshl_add_u64 v[84:85], v[40:41], 0, s[2:3]
	v_lshl_add_u64 v[86:87], v[38:39], 0, s[2:3]
	global_load_dword v88, v[72:73], off nt
	global_load_dword v89, v[74:75], off nt
	global_load_dword v90, v[76:77], off nt
	global_load_dword v91, v[78:79], off nt
	global_load_dword v92, v[80:81], off nt
	global_load_dword v93, v[82:83], off nt
	global_load_dword v94, v[84:85], off nt
	global_load_dword v95, v[86:87], off nt
	s_add_u32 s2, s2, 0x2000
	s_addc_u32 s3, s3, 0
	v_lshl_add_u64 v[72:73], v[52:53], 0, s[2:3]
	v_lshl_add_u64 v[74:75], v[50:51], 0, s[2:3]
	v_lshl_add_u64 v[76:77], v[48:49], 0, s[2:3]
	v_lshl_add_u64 v[78:79], v[46:47], 0, s[2:3]
	v_lshl_add_u64 v[80:81], v[44:45], 0, s[2:3]
	v_lshl_add_u64 v[82:83], v[42:43], 0, s[2:3]
	v_lshl_add_u64 v[84:85], v[40:41], 0, s[2:3]
	v_lshl_add_u64 v[86:87], v[38:39], 0, s[2:3]
	global_load_dword v96, v[72:73], off nt
	global_load_dword v97, v[74:75], off nt
	global_load_dword v98, v[76:77], off nt
	global_load_dword v99, v[78:79], off nt
	global_load_dword v100, v[80:81], off nt
	global_load_dword v101, v[82:83], off nt
	global_load_dword v102, v[84:85], off nt
	global_load_dword v103, v[86:87], off nt
	s_add_u32 s2, s2, 0x2000
	s_addc_u32 s3, s3, 0
	v_lshl_add_u64 v[72:73], v[52:53], 0, s[2:3]
	v_lshl_add_u64 v[74:75], v[50:51], 0, s[2:3]
	v_lshl_add_u64 v[76:77], v[48:49], 0, s[2:3]
	v_lshl_add_u64 v[78:79], v[46:47], 0, s[2:3]
	v_lshl_add_u64 v[80:81], v[44:45], 0, s[2:3]
	v_lshl_add_u64 v[82:83], v[42:43], 0, s[2:3]
	v_lshl_add_u64 v[84:85], v[40:41], 0, s[2:3]
	v_lshl_add_u64 v[86:87], v[38:39], 0, s[2:3]
	global_load_dword v104, v[72:73], off nt
	global_load_dword v105, v[74:75], off nt
	global_load_dword v106, v[76:77], off nt
	global_load_dword v107, v[78:79], off nt
	global_load_dword v108, v[80:81], off nt
	global_load_dword v109, v[82:83], off nt
	global_load_dword v110, v[84:85], off nt
	global_load_dword v111, v[86:87], off nt
	s_add_u32 s2, s2, 0x2000
	s_addc_u32 s3, s3, 0
	v_lshl_add_u64 v[72:73], v[52:53], 0, s[2:3]
	v_lshl_add_u64 v[74:75], v[50:51], 0, s[2:3]
	v_lshl_add_u64 v[76:77], v[48:49], 0, s[2:3]
	v_lshl_add_u64 v[78:79], v[46:47], 0, s[2:3]
	v_lshl_add_u64 v[80:81], v[44:45], 0, s[2:3]
	v_lshl_add_u64 v[82:83], v[42:43], 0, s[2:3]
	v_lshl_add_u64 v[84:85], v[40:41], 0, s[2:3]
	v_lshl_add_u64 v[86:87], v[38:39], 0, s[2:3]
	global_load_dword v112, v[72:73], off nt
	global_load_dword v113, v[74:75], off nt
	global_load_dword v114, v[76:77], off nt
	global_load_dword v115, v[78:79], off nt
	global_load_dword v116, v[80:81], off nt
	global_load_dword v117, v[82:83], off nt
	global_load_dword v118, v[84:85], off nt
	global_load_dword v119, v[86:87], off nt
	s_add_u32 s2, s2, 0x2000
	s_addc_u32 s3, s3, 0
	v_add_u32_e32 v79, 0x400, v0
	s_waitcnt vmcnt(30)
	ds_write2_b32 v0, v88, v89 offset1:66
	s_waitcnt vmcnt(28)
	ds_write2_b32 v0, v90, v91 offset0:132 offset1:198
	s_waitcnt vmcnt(26)
	ds_write2_b32 v79, v92, v93 offset0:8 offset1:74
	s_waitcnt vmcnt(24)
	ds_write2_b32 v79, v94, v95 offset0:140 offset1:206
	v_add_u32_e32 v0, 0x840, v0
	v_add_u32_e32 v79, 0x400, v0
	s_waitcnt vmcnt(22)
	ds_write2_b32 v0, v96, v97 offset1:66
	s_waitcnt vmcnt(20)
	ds_write2_b32 v0, v98, v99 offset0:132 offset1:198
	s_waitcnt vmcnt(18)
	ds_write2_b32 v79, v100, v101 offset0:8 offset1:74
	s_waitcnt vmcnt(16)
	ds_write2_b32 v79, v102, v103 offset0:140 offset1:206
	v_add_u32_e32 v0, 0x840, v0
	v_add_u32_e32 v79, 0x400, v0
	s_waitcnt vmcnt(14)
	ds_write2_b32 v0, v104, v105 offset1:66
	s_waitcnt vmcnt(12)
	ds_write2_b32 v0, v106, v107 offset0:132 offset1:198
	s_waitcnt vmcnt(10)
	ds_write2_b32 v79, v108, v109 offset0:8 offset1:74
	s_waitcnt vmcnt(8)
	ds_write2_b32 v79, v110, v111 offset0:140 offset1:206
	v_add_u32_e32 v0, 0x840, v0
	v_add_u32_e32 v79, 0x400, v0
	s_waitcnt vmcnt(6)
	ds_write2_b32 v0, v112, v113 offset1:66
	s_waitcnt vmcnt(4)
	ds_write2_b32 v0, v114, v115 offset0:132 offset1:198
	s_waitcnt vmcnt(2)
	ds_write2_b32 v79, v116, v117 offset0:8 offset1:74
	s_waitcnt vmcnt(0)
	ds_write2_b32 v79, v118, v119 offset0:140 offset1:206
	v_add_u32_e32 v0, 0x840, v0
	s_lshl_b32 s0, s12, 11
	s_add_i32 s0, s0, 0x7f140000
	s_waitcnt lgkmcnt(0)
; __device__ __forceinline__ unsigned pk2(float lo, float hi) { return f2bf(lo) | (f2bf(hi) << 16); }
; #define LAS __attribute__((address_space(3)))
; #define LDS_WAIT() asm volatile("s_waitcnt lgkmcnt(0)" ::: "memory")
;     ...
;     const int c = lane & 7;
; #pragma unroll
;     for (int j = 0; j < 4; ++j) { const int n = (lane >> 3) + 8 * j; const LAS float* s = scr + (8 * c) * 33 + n;
;         u32x4 o; o.x = pk2(s[0 * 33], s[1 * 33]); o.y = pk2(s[2 * 33], s[3 * 33]); o.z = pk2(s[4 * 33], s[5 * 33]); o.w = pk2(s[6 * 33], s[7 * 33]);
;         int rowd = r0 + n;
;         if (qkperm && n0 < 1280) rowd = (n0 & ~255) + 128 * ((n0 >> 5) & 1) + 32 * ((n0 >> 6) & 3) + qk_pos(n);
;         else if (qkperm && n0 >= 2048) { const int gcol = n0 - 2048 + n, half = gcol >> 10, c = gcol & 1023; rowd = 2048 + ((c >> 7) << 8) + 128 * half + (c & 127); }
;         *(u32x4*)(WT + (size_t)rowd * ldo + k0 + 8 * c) = o; }
;     LDS_WAIT(); asm volatile("" ::: "memory");
	s_and_b32 s0, s0, 0x7fffc000
	s_lshl_b32 s0, s0, 1
	ds_read2_b32 v[42:43], v56 offset1:8
	s_add_u32 s0, s26, s0
	ds_read2_b32 v[46:47], v56 offset0:33 offset1:41
	s_addc_u32 s3, s27, 0
	s_lshl_b32 s2, s12, 5
	s_and_b32 s2, s2, 0x80
	ds_read2_b32 v[48:49], v56 offset0:66 offset1:74
	s_add_u32 s2, s0, s2
	ds_read2_b32 v[50:51], v56 offset0:99 offset1:107
	s_addc_u32 s3, s3, 0
	v_mov_b32_e32 v37, v1
	s_waitcnt lgkmcnt(3)
	v_bfe_u32 v0, v42, 16, 1
	v_lshl_add_u64 v[44:45], s[2:3], 0, v[36:37]
	v_add3_u32 v0, v42, v0, s17
	s_waitcnt lgkmcnt(2)
	v_bfe_u32 v37, v46, 16, 1
	ds_read2_b32 v[52:53], v56 offset0:132 offset1:140
	v_lshrrev_b32_e32 v0, 16, v0
	v_add3_u32 v37, v46, v37, s17
	ds_read2_b32 v[72:73], v56 offset0:165 offset1:173
	v_and_or_b32 v38, v37, s19, v0
	s_waitcnt lgkmcnt(3)
	v_bfe_u32 v0, v48, 16, 1
	v_add3_u32 v0, v48, v0, s17
	s_waitcnt lgkmcnt(2)
	v_bfe_u32 v37, v50, 16, 1
	ds_read2_b32 v[74:75], v56 offset0:198 offset1:206
	v_lshrrev_b32_e32 v0, 16, v0
	v_add3_u32 v37, v50, v37, s17
	ds_read2_b32 v[76:77], v56 offset0:231 offset1:239
	v_and_or_b32 v39, v37, s19, v0
	s_waitcnt lgkmcnt(3)
	v_bfe_u32 v0, v52, 16, 1
	v_add3_u32 v0, v52, v0, s17
	s_waitcnt lgkmcnt(2)
	v_bfe_u32 v37, v72, 16, 1
	v_lshrrev_b32_e32 v0, 16, v0
	v_add3_u32 v37, v72, v37, s17
	v_and_or_b32 v40, v37, s19, v0
	s_waitcnt lgkmcnt(1)
	v_bfe_u32 v0, v74, 16, 1
	v_add3_u32 v0, v74, v0, s17
	s_waitcnt lgkmcnt(0)
	v_bfe_u32 v37, v76, 16, 1
	v_lshrrev_b32_e32 v0, 16, v0
	v_add3_u32 v37, v76, v37, s17
	v_and_or_b32 v41, v37, s19, v0
	v_bfe_u32 v0, v43, 16, 1
	v_add3_u32 v0, v43, v0, s17
	v_bfe_u32 v37, v47, 16, 1
	v_lshl_add_u64 v[78:79], v[44:45], 0, v[14:15]
	v_lshrrev_b32_e32 v0, 16, v0
	v_add3_u32 v37, v47, v37, s17
	global_store_dwordx4 v[78:79], v[38:41], off
	ds_read2_b32 v[42:43], v56 offset0:16 offset1:24
	v_lshl_add_u64 v[46:47], v[44:45], 0, v[16:17]
	v_and_or_b32 v38, v37, s19, v0
	v_bfe_u32 v0, v49, 16, 1
	v_add3_u32 v0, v49, v0, s17
	v_bfe_u32 v37, v51, 16, 1
	v_lshrrev_b32_e32 v0, 16, v0
	v_add3_u32 v37, v51, v37, s17
	v_and_or_b32 v39, v37, s19, v0
	v_bfe_u32 v0, v53, 16, 1
	v_add3_u32 v0, v53, v0, s17
	v_bfe_u32 v37, v73, 16, 1
	v_lshrrev_b32_e32 v0, 16, v0
	v_add3_u32 v37, v73, v37, s17
	v_and_or_b32 v40, v37, s19, v0
	v_bfe_u32 v0, v75, 16, 1
	v_add3_u32 v0, v75, v0, s17
	v_bfe_u32 v37, v77, 16, 1
	v_lshrrev_b32_e32 v0, 16, v0
	v_add3_u32 v37, v77, v37, s17
	v_and_or_b32 v41, v37, s19, v0
	global_store_dwordx4 v[46:47], v[38:41], off
	ds_read2_b32 v[46:47], v56 offset0:49 offset1:57
	ds_read2_b32 v[48:49], v56 offset0:82 offset1:90
	ds_read2_b32 v[50:51], v56 offset0:115 offset1:123
	s_waitcnt lgkmcnt(3)
	v_bfe_u32 v0, v42, 16, 1
	v_add3_u32 v0, v42, v0, s17
	s_waitcnt lgkmcnt(2)
	v_bfe_u32 v37, v46, 16, 1
	ds_read2_b32 v[52:53], v56 offset0:148 offset1:156
	v_lshrrev_b32_e32 v0, 16, v0
	v_add3_u32 v37, v46, v37, s17
	ds_read2_b32 v[72:73], v56 offset0:181 offset1:189
	v_and_or_b32 v38, v37, s19, v0
	s_waitcnt lgkmcnt(3)
	v_bfe_u32 v0, v48, 16, 1
	v_add3_u32 v0, v48, v0, s17
	s_waitcnt lgkmcnt(2)
	v_bfe_u32 v37, v50, 16, 1
	ds_read2_b32 v[74:75], v56 offset0:214 offset1:222
	v_lshrrev_b32_e32 v0, 16, v0
	v_add3_u32 v37, v50, v37, s17
	ds_read2_b32 v[76:77], v56 offset0:247 offset1:255
	v_and_or_b32 v39, v37, s19, v0
	s_waitcnt lgkmcnt(3)
	v_bfe_u32 v0, v52, 16, 1
	v_add3_u32 v0, v52, v0, s17
	s_waitcnt lgkmcnt(2)
	v_bfe_u32 v37, v72, 16, 1
	v_lshrrev_b32_e32 v0, 16, v0
	v_add3_u32 v37, v72, v37, s17
	v_and_or_b32 v40, v37, s19, v0
	s_waitcnt lgkmcnt(1)
	v_bfe_u32 v0, v74, 16, 1
	v_add3_u32 v0, v74, v0, s17
	s_waitcnt lgkmcnt(0)
	v_bfe_u32 v37, v76, 16, 1
	v_lshrrev_b32_e32 v0, 16, v0
	v_add3_u32 v37, v76, v37, s17
	v_and_or_b32 v41, v37, s19, v0
	v_bfe_u32 v37, v43, 16, 1
	v_bfe_u32 v0, v47, 16, 1
	v_add3_u32 v37, v43, v37, s17
	v_lshl_add_u64 v[78:79], v[44:45], 0, v[18:19]
	v_add3_u32 v0, v47, v0, s17
	v_lshrrev_b32_e32 v37, 16, v37
	global_store_dwordx4 v[78:79], v[38:41], off
	v_lshl_add_u64 v[42:43], v[44:45], 0, v[20:21]
	s_mov_b64 s[2:3], 0
	v_and_or_b32 v38, v0, s19, v37
	v_bfe_u32 v37, v49, 16, 1
	v_bfe_u32 v0, v51, 16, 1
	v_add3_u32 v37, v49, v37, s17
	v_add3_u32 v0, v51, v0, s17
	v_lshrrev_b32_e32 v37, 16, v37
	v_and_or_b32 v39, v0, s19, v37
	v_bfe_u32 v37, v53, 16, 1
	v_bfe_u32 v0, v73, 16, 1
	v_add3_u32 v37, v53, v37, s17
	v_add3_u32 v0, v73, v0, s17
	v_lshrrev_b32_e32 v37, 16, v37
	v_and_or_b32 v40, v0, s19, v37
	v_bfe_u32 v37, v75, 16, 1
	v_bfe_u32 v0, v77, 16, 1
	v_add3_u32 v37, v75, v37, s17
	v_add3_u32 v0, v77, v0, s17
	v_lshrrev_b32_e32 v37, 16, v37
	v_and_or_b32 v41, v0, s19, v37
	global_store_dwordx4 v[42:43], v[38:41], off
	s_waitcnt lgkmcnt(0)

; __device__ __forceinline__ unsigned pk2(float lo, float hi) { return f2bf(lo) | (f2bf(hi) << 16); }
; #define LAS __attribute__((address_space(3)))
; #define LDS_WAIT() asm volatile("s_waitcnt lgkmcnt(0)" ::: "memory")
;     ...
; #pragma unroll 8
;     for (int i = 0; i < 32; ++i) { const int kk = 2 * i + (lane >> 5); scr[kk * 33 + (lane & 31)] = __builtin_nontemporal_load(W + (size_t)(k0 + kk) * N + n0 + (lane & 31)); }
;     LDS_WAIT(); asm volatile("" ::: "memory");
;     int r0 = n0;
;     if (upmode) r0 = n0 < FF ? ((n0 >> 7) << 8) + (n0 & 127) : (((n0 - FF) >> 7) << 8) + 128 + ((n0 - FF) & 127);
;     const int c = lane & 7;
; #pragma unroll
;     for (int j = 0; j < 4; ++j) { const int n = (lane >> 3) + 8 * j; const LAS float* s = scr + (8 * c) * 33 + n;
;         u32x4 o; o.x = pk2(s[0 * 33], s[1 * 33]); o.y = pk2(s[2 * 33], s[3 * 33]); o.z = pk2(s[4 * 33], s[5 * 33]); o.w = pk2(s[6 * 33], s[7 * 33]);
.LBB9_44:
	v_lshl_add_u64 v[72:73], v[52:53], 0, s[2:3]
	v_lshl_add_u64 v[74:75], v[50:51], 0, s[2:3]
	v_lshl_add_u64 v[76:77], v[48:49], 0, s[2:3]
	v_lshl_add_u64 v[78:79], v[46:47], 0, s[2:3]
	v_lshl_add_u64 v[80:81], v[44:45], 0, s[2:3]
	v_lshl_add_u64 v[82:83], v[42:43], 0, s[2:3]
	v_lshl_add_u64 v[84:85], v[40:41], 0, s[2:3]
	v_lshl_add_u64 v[86:87], v[38:39], 0, s[2:3]
	global_load_dword v88, v[72:73], off nt
	global_load_dword v89, v[74:75], off nt
	global_load_dword v90, v[76:77], off nt
	global_load_dword v91, v[78:79], off nt
	global_load_dword v92, v[80:81], off nt
	global_load_dword v93, v[82:83], off nt
	global_load_dword v94, v[84:85], off nt
	global_load_dword v95, v[86:87], off nt
	s_add_u32 s2, s2, 0x10000
	s_addc_u32 s3, s3, 0
	v_lshl_add_u64 v[72:73], v[52:53], 0, s[2:3]
	v_lshl_add_u64 v[74:75], v[50:51], 0, s[2:3]
	v_lshl_add_u64 v[76:77], v[48:49], 0, s[2:3]
	v_lshl_add_u64 v[78:79], v[46:47], 0, s[2:3]
	v_lshl_add_u64 v[80:81], v[44:45], 0, s[2:3]
	v_lshl_add_u64 v[82:83], v[42:43], 0, s[2:3]
	v_lshl_add_u64 v[84:85], v[40:41], 0, s[2:3]
	v_lshl_add_u64 v[86:87], v[38:39], 0, s[2:3]
	global_load_dword v96, v[72:73], off nt
	global_load_dword v97, v[74:75], off nt
	global_load_dword v98, v[76:77], off nt
	global_load_dword v99, v[78:79], off nt
	global_load_dword v100, v[80:81], off nt
	global_load_dword v101, v[82:83], off nt
	global_load_dword v102, v[84:85], off nt
	global_load_dword v103, v[86:87], off nt
	s_add_u32 s2, s2, 0x10000
	s_addc_u32 s3, s3, 0
	v_lshl_add_u64 v[72:73], v[52:53], 0, s[2:3]
	v_lshl_add_u64 v[74:75], v[50:51], 0, s[2:3]
	v_lshl_add_u64 v[76:77], v[48:49], 0, s[2:3]
	v_lshl_add_u64 v[78:79], v[46:47], 0, s[2:3]
	v_lshl_add_u64 v[80:81], v[44:45], 0, s[2:3]
	v_lshl_add_u64 v[82:83], v[42:43], 0, s[2:3]
	v_lshl_add_u64 v[84:85], v[40:41], 0, s[2:3]
	v_lshl_add_u64 v[86:87], v[38:39], 0, s[2:3]
	global_load_dword v104, v[72:73], off nt
	global_load_dword v105, v[74:75], off nt
	global_load_dword v106, v[76:77], off nt
	global_load_dword v107, v[78:79], off nt
	global_load_dword v108, v[80:81], off nt
	global_load_dword v109, v[82:83], off nt
	global_load_dword v110, v[84:85], off nt
	global_load_dword v111, v[86:87], off nt
	s_add_u32 s2, s2, 0x10000
	s_addc_u32 s3, s3, 0
	v_lshl_add_u64 v[72:73], v[52:53], 0, s[2:3]
	v_lshl_add_u64 v[74:75], v[50:51], 0, s[2:3]
	v_lshl_add_u64 v[76:77], v[48:49], 0, s[2:3]
	v_lshl_add_u64 v[78:79], v[46:47], 0, s[2:3]
	v_lshl_add_u64 v[80:81], v[44:45], 0, s[2:3]
	v_lshl_add_u64 v[82:83], v[42:43], 0, s[2:3]
	v_lshl_add_u64 v[84:85], v[40:41], 0, s[2:3]
	v_lshl_add_u64 v[86:87], v[38:39], 0, s[2:3]
	global_load_dword v112, v[72:73], off nt
	global_load_dword v113, v[74:75], off nt
	global_load_dword v114, v[76:77], off nt
	global_load_dword v115, v[78:79], off nt
	global_load_dword v116, v[80:81], off nt
	global_load_dword v117, v[82:83], off nt
	global_load_dword v118, v[84:85], off nt
	global_load_dword v119, v[86:87], off nt
	s_add_u32 s2, s2, 0x10000
	s_addc_u32 s3, s3, 0
	v_add_u32_e32 v79, 0x400, v0
	s_waitcnt vmcnt(30)
	ds_write2_b32 v0, v88, v89 offset1:66
	s_waitcnt vmcnt(28)
	ds_write2_b32 v0, v90, v91 offset0:132 offset1:198
	s_waitcnt vmcnt(26)
	ds_write2_b32 v79, v92, v93 offset0:8 offset1:74
	s_waitcnt vmcnt(24)
	ds_write2_b32 v79, v94, v95 offset0:140 offset1:206
	v_add_u32_e32 v0, 0x840, v0
	v_add_u32_e32 v79, 0x400, v0
	s_waitcnt vmcnt(22)
	ds_write2_b32 v0, v96, v97 offset1:66
	s_waitcnt vmcnt(20)
	ds_write2_b32 v0, v98, v99 offset0:132 offset1:198
	s_waitcnt vmcnt(18)
	ds_write2_b32 v79, v100, v101 offset0:8 offset1:74
	s_waitcnt vmcnt(16)
	ds_write2_b32 v79, v102, v103 offset0:140 offset1:206
	v_add_u32_e32 v0, 0x840, v0
	v_add_u32_e32 v79, 0x400, v0
	s_waitcnt vmcnt(14)
	ds_write2_b32 v0, v104, v105 offset1:66
	s_waitcnt vmcnt(12)
	ds_write2_b32 v0, v106, v107 offset0:132 offset1:198
	s_waitcnt vmcnt(10)
	ds_write2_b32 v79, v108, v109 offset0:8 offset1:74
	s_waitcnt vmcnt(8)
	ds_write2_b32 v79, v110, v111 offset0:140 offset1:206
	v_add_u32_e32 v0, 0x840, v0
	v_add_u32_e32 v79, 0x400, v0
	s_waitcnt vmcnt(6)
	ds_write2_b32 v0, v112, v113 offset1:66
	s_waitcnt vmcnt(4)
	ds_write2_b32 v0, v114, v115 offset0:132 offset1:198
	s_waitcnt vmcnt(2)
	ds_write2_b32 v79, v116, v117 offset0:8 offset1:74
	s_waitcnt vmcnt(0)
	ds_write2_b32 v79, v118, v119 offset0:140 offset1:206
	v_add_u32_e32 v0, 0x840, v0
	s_waitcnt lgkmcnt(0)
	ds_read2_b32 v[42:43], v56 offset1:8
	ds_read2_b32 v[46:47], v56 offset0:33 offset1:41
	ds_read2_b32 v[48:49], v56 offset0:66 offset1:74
	ds_read2_b32 v[50:51], v56 offset0:99 offset1:107
	ds_read2_b32 v[52:53], v56 offset0:132 offset1:140
	s_waitcnt lgkmcnt(4)
; __device__ __forceinline__ unsigned pk2(float lo, float hi) { return f2bf(lo) | (f2bf(hi) << 16); }
; #define LAS __attribute__((address_space(3)))
; #define LDS_WAIT() asm volatile("s_waitcnt lgkmcnt(0)" ::: "memory")
;     ...
;     const int c = lane & 7;
; #pragma unroll
;     for (int j = 0; j < 4; ++j) { const int n = (lane >> 3) + 8 * j; const LAS float* s = scr + (8 * c) * 33 + n;
;         u32x4 o; o.x = pk2(s[0 * 33], s[1 * 33]); o.y = pk2(s[2 * 33], s[3 * 33]); o.z = pk2(s[4 * 33], s[5 * 33]); o.w = pk2(s[6 * 33], s[7 * 33]);
;         int rowd = r0 + n;
;         if (qkperm && n0 < 1280) rowd = (n0 & ~255) + 128 * ((n0 >> 5) & 1) + 32 * ((n0 >> 6) & 3) + qk_pos(n);
;         else if (qkperm && n0 >= 2048) { const int gcol = n0 - 2048 + n, half = gcol >> 10, c = gcol & 1023; rowd = 2048 + ((c >> 7) << 8) + 128 * half + (c & 127); }
;         *(u32x4*)(WT + (size_t)rowd * ldo + k0 + 8 * c) = o; }
;     LDS_WAIT(); asm volatile("" ::: "memory");
	v_bfe_u32 v0, v42, 16, 1
	v_add3_u32 v0, v42, v0, s17
	s_waitcnt lgkmcnt(3)
	v_bfe_u32 v37, v46, 16, 1
	v_lshrrev_b32_e32 v0, 16, v0
	v_add3_u32 v37, v46, v37, s17
	ds_read2_b32 v[72:73], v56 offset0:165 offset1:173
	v_and_or_b32 v38, v37, s19, v0
	s_waitcnt lgkmcnt(3)
	v_bfe_u32 v0, v48, 16, 1
	v_add3_u32 v0, v48, v0, s17
	s_waitcnt lgkmcnt(2)
	v_bfe_u32 v37, v50, 16, 1
	ds_read2_b32 v[74:75], v56 offset0:198 offset1:206
	v_lshrrev_b32_e32 v0, 16, v0
	v_add3_u32 v37, v50, v37, s17
	ds_read2_b32 v[76:77], v56 offset0:231 offset1:239
	v_and_or_b32 v39, v37, s19, v0
	s_waitcnt lgkmcnt(3)
	v_bfe_u32 v0, v52, 16, 1
	v_add3_u32 v0, v52, v0, s17
	s_waitcnt lgkmcnt(2)
	v_bfe_u32 v37, v72, 16, 1
	v_lshrrev_b32_e32 v0, 16, v0
	v_add3_u32 v37, v72, v37, s17
	v_and_or_b32 v40, v37, s19, v0
	s_waitcnt lgkmcnt(1)
	v_bfe_u32 v0, v74, 16, 1
	s_lshl_b32 s0, s12, 1
	s_lshl_b32 s2, s12, 5
	v_add3_u32 v0, v74, v0, s17
	s_waitcnt lgkmcnt(0)
	v_bfe_u32 v37, v76, 16, 1
	s_add_i32 s0, s0, 0x1d000
	s_and_b32 s2, s2, 0x3e0
	v_lshrrev_b32_e32 v0, 16, v0
	v_add3_u32 v37, v76, v37, s17
	s_and_b32 s0, s0, 0x1ffc0
	v_and_or_b32 v41, v37, s19, v0
	v_or_b32_e32 v0, s2, v55
	s_lshl_b32 s0, s0, 1
	v_mul_u32_u24_e32 v0, 0xb00, v0
	v_lshl_add_u64 v[44:45], v[2:3], 0, s[0:1]
	v_lshlrev_b32_e32 v0, 1, v0
	v_lshl_add_u64 v[78:79], v[44:45], 0, v[0:1]
	v_bfe_u32 v0, v43, 16, 1
	v_add3_u32 v0, v43, v0, s17
	v_bfe_u32 v37, v47, 16, 1
	v_lshrrev_b32_e32 v0, 16, v0
	v_add3_u32 v37, v47, v37, s17
	global_store_dwordx4 v[78:79], v[38:41], off
	ds_read2_b32 v[42:43], v56 offset0:16 offset1:24
	s_nop 0
	v_and_or_b32 v38, v37, s19, v0
	v_bfe_u32 v0, v49, 16, 1
	v_add3_u32 v0, v49, v0, s17
	v_bfe_u32 v37, v51, 16, 1
	v_lshrrev_b32_e32 v0, 16, v0
	v_add3_u32 v37, v51, v37, s17
	v_and_or_b32 v39, v37, s19, v0
	v_bfe_u32 v0, v53, 16, 1
	v_add3_u32 v0, v53, v0, s17
	v_bfe_u32 v37, v73, 16, 1
	v_lshrrev_b32_e32 v0, 16, v0
	v_add3_u32 v37, v73, v37, s17
	v_and_or_b32 v40, v37, s19, v0
	v_bfe_u32 v0, v75, 16, 1
	v_add3_u32 v0, v75, v0, s17
	v_bfe_u32 v37, v77, 16, 1
	v_lshrrev_b32_e32 v0, 16, v0
	v_add3_u32 v37, v77, v37, s17
	v_and_or_b32 v41, v37, s19, v0
	v_or_b32_e32 v0, s2, v57
	v_mul_u32_u24_e32 v0, 0xb00, v0
	v_lshlrev_b32_e32 v0, 1, v0
	v_lshl_add_u64 v[46:47], v[44:45], 0, v[0:1]
	global_store_dwordx4 v[46:47], v[38:41], off
	ds_read2_b32 v[46:47], v56 offset0:49 offset1:57
	ds_read2_b32 v[48:49], v56 offset0:82 offset1:90
	ds_read2_b32 v[50:51], v56 offset0:115 offset1:123
	s_waitcnt lgkmcnt(3)
	v_bfe_u32 v0, v42, 16, 1
	v_add3_u32 v0, v42, v0, s17
	s_waitcnt lgkmcnt(2)
	v_bfe_u32 v37, v46, 16, 1
	ds_read2_b32 v[52:53], v56 offset0:148 offset1:156
	v_lshrrev_b32_e32 v0, 16, v0
	v_add3_u32 v37, v46, v37, s17
	ds_read2_b32 v[72:73], v56 offset0:181 offset1:189
	v_and_or_b32 v38, v37, s19, v0
	s_waitcnt lgkmcnt(3)
	v_bfe_u32 v0, v48, 16, 1
	v_add3_u32 v0, v48, v0, s17
	s_waitcnt lgkmcnt(2)
	v_bfe_u32 v37, v50, 16, 1
	ds_read2_b32 v[74:75], v56 offset0:214 offset1:222
	v_lshrrev_b32_e32 v0, 16, v0
	v_add3_u32 v37, v50, v37, s17
	ds_read2_b32 v[76:77], v56 offset0:247 offset1:255
	v_and_or_b32 v39, v37, s19, v0
	s_waitcnt lgkmcnt(3)
	v_bfe_u32 v0, v52, 16, 1
	v_add3_u32 v0, v52, v0, s17
	s_waitcnt lgkmcnt(2)
	v_bfe_u32 v37, v72, 16, 1
	v_lshrrev_b32_e32 v0, 16, v0
	v_add3_u32 v37, v72, v37, s17
	v_and_or_b32 v40, v37, s19, v0
	s_waitcnt lgkmcnt(1)
	v_bfe_u32 v0, v74, 16, 1
	v_add3_u32 v0, v74, v0, s17
	s_waitcnt lgkmcnt(0)
	v_bfe_u32 v37, v76, 16, 1
	v_lshrrev_b32_e32 v0, 16, v0
	v_add3_u32 v37, v76, v37, s17
	v_and_or_b32 v41, v37, s19, v0
	v_or_b32_e32 v0, s2, v58
	v_mul_u32_u24_e32 v0, 0xb00, v0
	v_lshlrev_b32_e32 v0, 1, v0
	v_lshl_add_u64 v[78:79], v[44:45], 0, v[0:1]
	global_store_dwordx4 v[78:79], v[38:41], off
	v_bfe_u32 v37, v47, 16, 1
	v_add3_u32 v37, v47, v37, s17
	v_bfe_u32 v38, v43, 16, 1
	v_add3_u32 v38, v43, v38, s17
	v_lshrrev_b32_e32 v38, 16, v38
	v_bfe_u32 v39, v49, 16, 1
	v_and_or_b32 v38, v37, s19, v38
	v_bfe_u32 v37, v51, 16, 1
	v_add3_u32 v39, v49, v39, s17
	v_add3_u32 v37, v51, v37, s17
	v_lshrrev_b32_e32 v39, 16, v39
	v_bfe_u32 v40, v53, 16, 1
	v_and_or_b32 v39, v37, s19, v39
	v_bfe_u32 v37, v73, 16, 1
	v_add3_u32 v40, v53, v40, s17
	v_or_b32_e32 v0, s2, v59
	v_add3_u32 v37, v73, v37, s17
	v_lshrrev_b32_e32 v40, 16, v40
	v_bfe_u32 v41, v75, 16, 1
	v_and_or_b32 v40, v37, s19, v40
	v_bfe_u32 v37, v77, 16, 1
	v_add3_u32 v41, v75, v41, s17
	v_mul_u32_u24_e32 v0, 0xb00, v0
	v_add3_u32 v37, v77, v37, s17
	v_lshrrev_b32_e32 v41, 16, v41
	v_lshlrev_b32_e32 v0, 1, v0
	v_and_or_b32 v41, v37, s19, v41
	v_lshl_add_u64 v[42:43], v[44:45], 0, v[0:1]
	global_store_dwordx4 v[42:43], v[38:41], off
	s_waitcnt lgkmcnt(0)

; __device__ __forceinline__ unsigned pk2(float lo, float hi) { return f2bf(lo) | (f2bf(hi) << 16); }
; #define LAS __attribute__((address_space(3)))
; #define LDS_WAIT() asm volatile("s_waitcnt lgkmcnt(0)" ::: "memory")
;     ...
; #pragma unroll 8
;     for (int i = 0; i < 32; ++i) { const int kk = 2 * i + (lane >> 5); scr[kk * 33 + (lane & 31)] = __builtin_nontemporal_load(W + (size_t)(k0 + kk) * N + n0 + (lane & 31)); }
;     LDS_WAIT(); asm volatile("" ::: "memory");
;     int r0 = n0;
;     if (upmode) r0 = n0 < FF ? ((n0 >> 7) << 8) + (n0 & 127) : (((n0 - FF) >> 7) << 8) + 128 + ((n0 - FF) & 127);
;     const int c = lane & 7;
; #pragma unroll
;     for (int j = 0; j < 4; ++j) { const int n = (lane >> 3) + 8 * j; const LAS float* s = scr + (8 * c) * 33 + n;
;         u32x4 o; o.x = pk2(s[0 * 33], s[1 * 33]); o.y = pk2(s[2 * 33], s[3 * 33]); o.z = pk2(s[4 * 33], s[5 * 33]); o.w = pk2(s[6 * 33], s[7 * 33]);
.LBB9_49:
	v_lshl_add_u64 v[72:73], v[52:53], 0, s[2:3]
	v_lshl_add_u64 v[74:75], v[50:51], 0, s[2:3]
	v_lshl_add_u64 v[76:77], v[48:49], 0, s[2:3]
	v_lshl_add_u64 v[78:79], v[46:47], 0, s[2:3]
	v_lshl_add_u64 v[80:81], v[44:45], 0, s[2:3]
	v_lshl_add_u64 v[82:83], v[42:43], 0, s[2:3]
	v_lshl_add_u64 v[84:85], v[40:41], 0, s[2:3]
	v_lshl_add_u64 v[86:87], v[38:39], 0, s[2:3]
	global_load_dword v88, v[72:73], off nt
	global_load_dword v89, v[74:75], off nt
	global_load_dword v90, v[76:77], off nt
	global_load_dword v91, v[78:79], off nt
	global_load_dword v92, v[80:81], off nt
	global_load_dword v93, v[82:83], off nt
	global_load_dword v94, v[84:85], off nt
	global_load_dword v95, v[86:87], off nt
	s_add_u32 s2, s2, 0x58000
	s_addc_u32 s3, s3, 0
	v_lshl_add_u64 v[72:73], v[52:53], 0, s[2:3]
	v_lshl_add_u64 v[74:75], v[50:51], 0, s[2:3]
	v_lshl_add_u64 v[76:77], v[48:49], 0, s[2:3]
	v_lshl_add_u64 v[78:79], v[46:47], 0, s[2:3]
	v_lshl_add_u64 v[80:81], v[44:45], 0, s[2:3]
	v_lshl_add_u64 v[82:83], v[42:43], 0, s[2:3]
	v_lshl_add_u64 v[84:85], v[40:41], 0, s[2:3]
	v_lshl_add_u64 v[86:87], v[38:39], 0, s[2:3]
	global_load_dword v96, v[72:73], off nt
	global_load_dword v97, v[74:75], off nt
	global_load_dword v98, v[76:77], off nt
	global_load_dword v99, v[78:79], off nt
	global_load_dword v100, v[80:81], off nt
	global_load_dword v101, v[82:83], off nt
	global_load_dword v102, v[84:85], off nt
	global_load_dword v103, v[86:87], off nt
	s_add_u32 s2, s2, 0x58000
	s_addc_u32 s3, s3, 0
	v_lshl_add_u64 v[72:73], v[52:53], 0, s[2:3]
	v_lshl_add_u64 v[74:75], v[50:51], 0, s[2:3]
	v_lshl_add_u64 v[76:77], v[48:49], 0, s[2:3]
	v_lshl_add_u64 v[78:79], v[46:47], 0, s[2:3]
	v_lshl_add_u64 v[80:81], v[44:45], 0, s[2:3]
	v_lshl_add_u64 v[82:83], v[42:43], 0, s[2:3]
	v_lshl_add_u64 v[84:85], v[40:41], 0, s[2:3]
	v_lshl_add_u64 v[86:87], v[38:39], 0, s[2:3]
	global_load_dword v104, v[72:73], off nt
	global_load_dword v105, v[74:75], off nt
	global_load_dword v106, v[76:77], off nt
	global_load_dword v107, v[78:79], off nt
	global_load_dword v108, v[80:81], off nt
	global_load_dword v109, v[82:83], off nt
	global_load_dword v110, v[84:85], off nt
	global_load_dword v111, v[86:87], off nt
	s_add_u32 s2, s2, 0x58000
	s_addc_u32 s3, s3, 0
	v_lshl_add_u64 v[72:73], v[52:53], 0, s[2:3]
	v_lshl_add_u64 v[74:75], v[50:51], 0, s[2:3]
	v_lshl_add_u64 v[76:77], v[48:49], 0, s[2:3]
	v_lshl_add_u64 v[78:79], v[46:47], 0, s[2:3]
	v_lshl_add_u64 v[80:81], v[44:45], 0, s[2:3]
	v_lshl_add_u64 v[82:83], v[42:43], 0, s[2:3]
	v_lshl_add_u64 v[84:85], v[40:41], 0, s[2:3]
	v_lshl_add_u64 v[86:87], v[38:39], 0, s[2:3]
	global_load_dword v112, v[72:73], off nt
	global_load_dword v113, v[74:75], off nt
	global_load_dword v114, v[76:77], off nt
	global_load_dword v115, v[78:79], off nt
	global_load_dword v116, v[80:81], off nt
	global_load_dword v117, v[82:83], off nt
	global_load_dword v118, v[84:85], off nt
	global_load_dword v119, v[86:87], off nt
	s_add_u32 s2, s2, 0x58000
	s_addc_u32 s3, s3, 0
	v_add_u32_e32 v79, 0x400, v0
	s_waitcnt vmcnt(30)
	ds_write2_b32 v0, v88, v89 offset1:66
	s_waitcnt vmcnt(28)
	ds_write2_b32 v0, v90, v91 offset0:132 offset1:198
	s_waitcnt vmcnt(26)
	ds_write2_b32 v79, v92, v93 offset0:8 offset1:74
	s_waitcnt vmcnt(24)
	ds_write2_b32 v79, v94, v95 offset0:140 offset1:206
	v_add_u32_e32 v0, 0x840, v0
	v_add_u32_e32 v79, 0x400, v0
	s_waitcnt vmcnt(22)
	ds_write2_b32 v0, v96, v97 offset1:66
	s_waitcnt vmcnt(20)
	ds_write2_b32 v0, v98, v99 offset0:132 offset1:198
	s_waitcnt vmcnt(18)
	ds_write2_b32 v79, v100, v101 offset0:8 offset1:74
	s_waitcnt vmcnt(16)
	ds_write2_b32 v79, v102, v103 offset0:140 offset1:206
	v_add_u32_e32 v0, 0x840, v0
	v_add_u32_e32 v79, 0x400, v0
	s_waitcnt vmcnt(14)
	ds_write2_b32 v0, v104, v105 offset1:66
	s_waitcnt vmcnt(12)
	ds_write2_b32 v0, v106, v107 offset0:132 offset1:198
	s_waitcnt vmcnt(10)
	ds_write2_b32 v79, v108, v109 offset0:8 offset1:74
	s_waitcnt vmcnt(8)
	ds_write2_b32 v79, v110, v111 offset0:140 offset1:206
	v_add_u32_e32 v0, 0x840, v0
	v_add_u32_e32 v79, 0x400, v0
	s_waitcnt vmcnt(6)
	ds_write2_b32 v0, v112, v113 offset1:66
	s_waitcnt vmcnt(4)
	ds_write2_b32 v0, v114, v115 offset0:132 offset1:198
	s_waitcnt vmcnt(2)
	ds_write2_b32 v79, v116, v117 offset0:8 offset1:74
	s_waitcnt vmcnt(0)
	ds_write2_b32 v79, v118, v119 offset0:140 offset1:206
	v_add_u32_e32 v0, 0x840, v0
	s_waitcnt lgkmcnt(0)
	ds_read2_b32 v[42:43], v56 offset1:8
	ds_read2_b32 v[46:47], v56 offset0:33 offset1:41
	ds_read2_b32 v[48:49], v56 offset0:66 offset1:74
	ds_read2_b32 v[50:51], v56 offset0:99 offset1:107
	ds_read2_b32 v[52:53], v56 offset0:132 offset1:140
	s_waitcnt lgkmcnt(4)
	v_bfe_u32 v0, v42, 16, 1
	v_add3_u32 v0, v42, v0, s17
	s_waitcnt lgkmcnt(3)
; __device__ __forceinline__ unsigned pk2(float lo, float hi) { return f2bf(lo) | (f2bf(hi) << 16); }
; #define LAS __attribute__((address_space(3)))
; #define LDS_WAIT() asm volatile("s_waitcnt lgkmcnt(0)" ::: "memory")
;     ...
;     if (upmode) r0 = n0 < FF ? ((n0 >> 7) << 8) + (n0 & 127) : (((n0 - FF) >> 7) << 8) + 128 + ((n0 - FF) & 127);
;     const int c = lane & 7;
; #pragma unroll
;     for (int j = 0; j < 4; ++j) { const int n = (lane >> 3) + 8 * j; const LAS float* s = scr + (8 * c) * 33 + n;
;         u32x4 o; o.x = pk2(s[0 * 33], s[1 * 33]); o.y = pk2(s[2 * 33], s[3 * 33]); o.z = pk2(s[4 * 33], s[5 * 33]); o.w = pk2(s[6 * 33], s[7 * 33]);
;         int rowd = r0 + n;
;         if (qkperm && n0 < 1280) rowd = (n0 & ~255) + 128 * ((n0 >> 5) & 1) + 32 * ((n0 >> 6) & 3) + qk_pos(n);
;         else if (qkperm && n0 >= 2048) { const int gcol = n0 - 2048 + n, half = gcol >> 10, c = gcol & 1023; rowd = 2048 + ((c >> 7) << 8) + 128 * half + (c & 127); }
;         *(u32x4*)(WT + (size_t)rowd * ldo + k0 + 8 * c) = o; }
;     LDS_WAIT(); asm volatile("" ::: "memory");
	v_bfe_u32 v37, v46, 16, 1
	v_lshrrev_b32_e32 v0, 16, v0
	v_add3_u32 v37, v46, v37, s17
	ds_read2_b32 v[72:73], v56 offset0:165 offset1:173
	v_and_or_b32 v38, v37, s19, v0
	s_waitcnt lgkmcnt(3)
	v_bfe_u32 v0, v48, 16, 1
	v_add3_u32 v0, v48, v0, s17
	s_waitcnt lgkmcnt(2)
	v_bfe_u32 v37, v50, 16, 1
	ds_read2_b32 v[74:75], v56 offset0:198 offset1:206
	s_lshl_b32 s0, s10, 6
	v_lshrrev_b32_e32 v0, 16, v0
	v_add3_u32 v37, v50, v37, s17
	ds_read2_b32 v[76:77], v56 offset0:231 offset1:239
	s_and_b32 s2, s0, 0x1f00
	s_and_b32 s0, s0, 0x3f00
	v_and_or_b32 v39, v37, s19, v0
	s_waitcnt lgkmcnt(3)
	v_bfe_u32 v0, v52, 16, 1
	s_addk_i32 s0, 0xea80
	v_add3_u32 v0, v52, v0, s17
	s_waitcnt lgkmcnt(2)
	v_bfe_u32 v37, v72, 16, 1
	s_cmpk_lt_u32 s10, 0x58
	v_lshrrev_b32_e32 v0, 16, v0
	v_add3_u32 v37, v72, v37, s17
	s_cselect_b32 s0, s2, s0
	s_and_b32 s2, s11, 0x60
	v_and_or_b32 v40, v37, s19, v0
	s_waitcnt lgkmcnt(1)
	v_bfe_u32 v0, v74, 16, 1
	s_or_b32 s2, s0, s2
	v_add3_u32 v0, v74, v0, s17
	s_waitcnt lgkmcnt(0)
	v_bfe_u32 v37, v76, 16, 1
	s_and_b32 s0, 0xffff, s9
	v_lshrrev_b32_e32 v0, 16, v0
	v_add3_u32 v37, v76, v37, s17
	v_or_b32_e32 v78, s2, v55
	s_lshl_b32 s0, s0, 1
	v_and_or_b32 v41, v37, s19, v0
	v_ashrrev_i32_e32 v79, 31, v78
	v_bfe_u32 v0, v43, 16, 1
	v_lshl_add_u64 v[44:45], v[4:5], 0, s[0:1]
	v_lshlrev_b64 v[78:79], 11, v[78:79]
	v_add3_u32 v0, v43, v0, s17
	v_bfe_u32 v37, v47, 16, 1
	v_lshl_add_u64 v[78:79], v[44:45], 0, v[78:79]
	v_lshrrev_b32_e32 v0, 16, v0
	v_add3_u32 v37, v47, v37, s17
	global_store_dwordx4 v[78:79], v[38:41], off
	v_or_b32_e32 v42, s2, v57
	v_ashrrev_i32_e32 v43, 31, v42
	v_and_or_b32 v38, v37, s19, v0
	v_bfe_u32 v0, v49, 16, 1
	v_add3_u32 v0, v49, v0, s17
	v_bfe_u32 v37, v51, 16, 1
	v_lshrrev_b32_e32 v0, 16, v0
	v_add3_u32 v37, v51, v37, s17
	v_and_or_b32 v39, v37, s19, v0
	v_bfe_u32 v0, v53, 16, 1
	v_add3_u32 v0, v53, v0, s17
	v_bfe_u32 v37, v73, 16, 1
	v_lshrrev_b32_e32 v0, 16, v0
	v_add3_u32 v37, v73, v37, s17
	v_and_or_b32 v40, v37, s19, v0
	v_bfe_u32 v0, v75, 16, 1
	v_add3_u32 v0, v75, v0, s17
	v_bfe_u32 v37, v77, 16, 1
	v_lshrrev_b32_e32 v0, 16, v0
	v_add3_u32 v37, v77, v37, s17
	v_lshlrev_b64 v[42:43], 11, v[42:43]
	v_and_or_b32 v41, v37, s19, v0
	ds_read2_b32 v[46:47], v56 offset0:16 offset1:24
	v_lshl_add_u64 v[42:43], v[44:45], 0, v[42:43]
	global_store_dwordx4 v[42:43], v[38:41], off
	ds_read2_b32 v[42:43], v56 offset0:49 offset1:57
	ds_read2_b32 v[48:49], v56 offset0:82 offset1:90
	ds_read2_b32 v[50:51], v56 offset0:115 offset1:123
	s_waitcnt lgkmcnt(3)
	v_bfe_u32 v0, v46, 16, 1
	v_add3_u32 v0, v46, v0, s17
	s_waitcnt lgkmcnt(2)
	v_bfe_u32 v37, v42, 16, 1
	ds_read2_b32 v[52:53], v56 offset0:148 offset1:156
	v_lshrrev_b32_e32 v0, 16, v0
	v_add3_u32 v37, v42, v37, s17
	ds_read2_b32 v[72:73], v56 offset0:181 offset1:189
	v_and_or_b32 v38, v37, s19, v0
	s_waitcnt lgkmcnt(3)
	v_bfe_u32 v0, v48, 16, 1
	v_add3_u32 v0, v48, v0, s17
	s_waitcnt lgkmcnt(2)
	v_bfe_u32 v37, v50, 16, 1
	ds_read2_b32 v[74:75], v56 offset0:214 offset1:222
	v_lshrrev_b32_e32 v0, 16, v0
	v_add3_u32 v37, v50, v37, s17
	ds_read2_b32 v[76:77], v56 offset0:247 offset1:255
	v_and_or_b32 v39, v37, s19, v0
	s_waitcnt lgkmcnt(3)
	v_bfe_u32 v0, v52, 16, 1
	v_add3_u32 v0, v52, v0, s17
	s_waitcnt lgkmcnt(2)
	v_bfe_u32 v37, v72, 16, 1
	v_lshrrev_b32_e32 v0, 16, v0
	v_add3_u32 v37, v72, v37, s17
	v_and_or_b32 v40, v37, s19, v0
	s_waitcnt lgkmcnt(1)
	v_bfe_u32 v0, v74, 16, 1
	v_add3_u32 v0, v74, v0, s17
	s_waitcnt lgkmcnt(0)
	v_bfe_u32 v37, v76, 16, 1
	v_lshrrev_b32_e32 v0, 16, v0
	v_add3_u32 v37, v76, v37, s17
	v_or_b32_e32 v78, s2, v58
	v_and_or_b32 v41, v37, s19, v0
	v_ashrrev_i32_e32 v79, 31, v78
	v_bfe_u32 v37, v47, 16, 1
	v_lshlrev_b64 v[78:79], 11, v[78:79]
	v_bfe_u32 v0, v43, 16, 1
	v_add3_u32 v37, v47, v37, s17
	v_lshl_add_u64 v[78:79], v[44:45], 0, v[78:79]
	v_add3_u32 v0, v43, v0, s17
	v_lshrrev_b32_e32 v37, 16, v37
	global_store_dwordx4 v[78:79], v[38:41], off
	v_or_b32_e32 v42, s2, v59
	v_ashrrev_i32_e32 v43, 31, v42
	v_and_or_b32 v38, v0, s19, v37
	v_bfe_u32 v37, v49, 16, 1
	v_bfe_u32 v0, v51, 16, 1
	v_add3_u32 v37, v49, v37, s17
	v_add3_u32 v0, v51, v0, s17
	v_lshrrev_b32_e32 v37, 16, v37
	v_and_or_b32 v39, v0, s19, v37
	v_bfe_u32 v37, v53, 16, 1
	v_bfe_u32 v0, v73, 16, 1
	v_add3_u32 v37, v53, v37, s17
	v_add3_u32 v0, v73, v0, s17
	v_lshrrev_b32_e32 v37, 16, v37
	v_and_or_b32 v40, v0, s19, v37
	v_bfe_u32 v37, v75, 16, 1
	v_bfe_u32 v0, v77, 16, 1
	v_add3_u32 v37, v75, v37, s17
	v_add3_u32 v0, v77, v0, s17
	v_lshrrev_b32_e32 v37, 16, v37
	v_lshlrev_b64 v[42:43], 11, v[42:43]
	v_and_or_b32 v41, v0, s19, v37
	v_lshl_add_u64 v[42:43], v[44:45], 0, v[42:43]
	global_store_dwordx4 v[42:43], v[38:41], off
	s_waitcnt lgkmcnt(0)

; __device__ __forceinline__ unsigned pk2(float lo, float hi) { return f2bf(lo) | (f2bf(hi) << 16); }
; #define LAS __attribute__((address_space(3)))
; #define LDS_WAIT() asm volatile("s_waitcnt lgkmcnt(0)" ::: "memory")
;     ...
; #pragma unroll 8
;     for (int i = 0; i < 32; ++i) { const int kk = 2 * i + (lane >> 5); scr[kk * 33 + (lane & 31)] = __builtin_nontemporal_load(W + (size_t)(k0 + kk) * N + n0 + (lane & 31)); }
;     LDS_WAIT(); asm volatile("" ::: "memory");
;     int r0 = n0;
;     if (upmode) r0 = n0 < FF ? ((n0 >> 7) << 8) + (n0 & 127) : (((n0 - FF) >> 7) << 8) + 128 + ((n0 - FF) & 127);
;     const int c = lane & 7;
; #pragma unroll
;     for (int j = 0; j < 4; ++j) { const int n = (lane >> 3) + 8 * j; const LAS float* s = scr + (8 * c) * 33 + n;
;         u32x4 o; o.x = pk2(s[0 * 33], s[1 * 33]); o.y = pk2(s[2 * 33], s[3 * 33]); o.z = pk2(s[4 * 33], s[5 * 33]); o.w = pk2(s[6 * 33], s[7 * 33]);
.LBB9_54:
	v_lshl_add_u64 v[72:73], v[52:53], 0, s[2:3]
	v_lshl_add_u64 v[74:75], v[50:51], 0, s[2:3]
	v_lshl_add_u64 v[76:77], v[48:49], 0, s[2:3]
	v_lshl_add_u64 v[78:79], v[46:47], 0, s[2:3]
	v_lshl_add_u64 v[80:81], v[44:45], 0, s[2:3]
	v_lshl_add_u64 v[82:83], v[42:43], 0, s[2:3]
	v_lshl_add_u64 v[84:85], v[40:41], 0, s[2:3]
	v_lshl_add_u64 v[86:87], v[38:39], 0, s[2:3]
	global_load_dword v88, v[72:73], off nt
	global_load_dword v89, v[74:75], off nt
	global_load_dword v90, v[76:77], off nt
	global_load_dword v91, v[78:79], off nt
	global_load_dword v92, v[80:81], off nt
	global_load_dword v93, v[82:83], off nt
	global_load_dword v94, v[84:85], off nt
	global_load_dword v95, v[86:87], off nt
	s_add_u32 s2, s2, 0x10000
	s_addc_u32 s3, s3, 0
	v_lshl_add_u64 v[72:73], v[52:53], 0, s[2:3]
	v_lshl_add_u64 v[74:75], v[50:51], 0, s[2:3]
	v_lshl_add_u64 v[76:77], v[48:49], 0, s[2:3]
	v_lshl_add_u64 v[78:79], v[46:47], 0, s[2:3]
	v_lshl_add_u64 v[80:81], v[44:45], 0, s[2:3]
	v_lshl_add_u64 v[82:83], v[42:43], 0, s[2:3]
	v_lshl_add_u64 v[84:85], v[40:41], 0, s[2:3]
	v_lshl_add_u64 v[86:87], v[38:39], 0, s[2:3]
	global_load_dword v96, v[72:73], off nt
	global_load_dword v97, v[74:75], off nt
	global_load_dword v98, v[76:77], off nt
	global_load_dword v99, v[78:79], off nt
	global_load_dword v100, v[80:81], off nt
	global_load_dword v101, v[82:83], off nt
	global_load_dword v102, v[84:85], off nt
	global_load_dword v103, v[86:87], off nt
	s_add_u32 s2, s2, 0x10000
	s_addc_u32 s3, s3, 0
	v_lshl_add_u64 v[72:73], v[52:53], 0, s[2:3]
	v_lshl_add_u64 v[74:75], v[50:51], 0, s[2:3]
	v_lshl_add_u64 v[76:77], v[48:49], 0, s[2:3]
	v_lshl_add_u64 v[78:79], v[46:47], 0, s[2:3]
	v_lshl_add_u64 v[80:81], v[44:45], 0, s[2:3]
	v_lshl_add_u64 v[82:83], v[42:43], 0, s[2:3]
	v_lshl_add_u64 v[84:85], v[40:41], 0, s[2:3]
	v_lshl_add_u64 v[86:87], v[38:39], 0, s[2:3]
	global_load_dword v104, v[72:73], off nt
	global_load_dword v105, v[74:75], off nt
	global_load_dword v106, v[76:77], off nt
	global_load_dword v107, v[78:79], off nt
	global_load_dword v108, v[80:81], off nt
	global_load_dword v109, v[82:83], off nt
	global_load_dword v110, v[84:85], off nt
	global_load_dword v111, v[86:87], off nt
	s_add_u32 s2, s2, 0x10000
	s_addc_u32 s3, s3, 0
	v_lshl_add_u64 v[72:73], v[52:53], 0, s[2:3]
	v_lshl_add_u64 v[74:75], v[50:51], 0, s[2:3]
	v_lshl_add_u64 v[76:77], v[48:49], 0, s[2:3]
	v_lshl_add_u64 v[78:79], v[46:47], 0, s[2:3]
	v_lshl_add_u64 v[80:81], v[44:45], 0, s[2:3]
	v_lshl_add_u64 v[82:83], v[42:43], 0, s[2:3]
	v_lshl_add_u64 v[84:85], v[40:41], 0, s[2:3]
	v_lshl_add_u64 v[86:87], v[38:39], 0, s[2:3]
	global_load_dword v112, v[72:73], off nt
	global_load_dword v113, v[74:75], off nt
	global_load_dword v114, v[76:77], off nt
	global_load_dword v115, v[78:79], off nt
	global_load_dword v116, v[80:81], off nt
	global_load_dword v117, v[82:83], off nt
	global_load_dword v118, v[84:85], off nt
	global_load_dword v119, v[86:87], off nt
	s_add_u32 s2, s2, 0x10000
	s_addc_u32 s3, s3, 0
	v_add_u32_e32 v79, 0x400, v0
	s_waitcnt vmcnt(30)
	ds_write2_b32 v0, v88, v89 offset1:66
	s_waitcnt vmcnt(28)
	ds_write2_b32 v0, v90, v91 offset0:132 offset1:198
	s_waitcnt vmcnt(26)
	ds_write2_b32 v79, v92, v93 offset0:8 offset1:74
	s_waitcnt vmcnt(24)
	ds_write2_b32 v79, v94, v95 offset0:140 offset1:206
	v_add_u32_e32 v0, 0x840, v0
	v_add_u32_e32 v79, 0x400, v0
	s_waitcnt vmcnt(22)
	ds_write2_b32 v0, v96, v97 offset1:66
	s_waitcnt vmcnt(20)
	ds_write2_b32 v0, v98, v99 offset0:132 offset1:198
	s_waitcnt vmcnt(18)
	ds_write2_b32 v79, v100, v101 offset0:8 offset1:74
	s_waitcnt vmcnt(16)
	ds_write2_b32 v79, v102, v103 offset0:140 offset1:206
	v_add_u32_e32 v0, 0x840, v0
	v_add_u32_e32 v79, 0x400, v0
	s_waitcnt vmcnt(14)
	ds_write2_b32 v0, v104, v105 offset1:66
	s_waitcnt vmcnt(12)
	ds_write2_b32 v0, v106, v107 offset0:132 offset1:198
	s_waitcnt vmcnt(10)
	ds_write2_b32 v79, v108, v109 offset0:8 offset1:74
	s_waitcnt vmcnt(8)
	ds_write2_b32 v79, v110, v111 offset0:140 offset1:206
	v_add_u32_e32 v0, 0x840, v0
	v_add_u32_e32 v79, 0x400, v0
	s_waitcnt vmcnt(6)
	ds_write2_b32 v0, v112, v113 offset1:66
	s_waitcnt vmcnt(4)
	ds_write2_b32 v0, v114, v115 offset0:132 offset1:198
	s_waitcnt vmcnt(2)
	ds_write2_b32 v79, v116, v117 offset0:8 offset1:74
	s_waitcnt vmcnt(0)
	ds_write2_b32 v79, v118, v119 offset0:140 offset1:206
	v_add_u32_e32 v0, 0x840, v0
	s_waitcnt lgkmcnt(0)
	ds_read2_b32 v[42:43], v56 offset1:8
	ds_read2_b32 v[46:47], v56 offset0:33 offset1:41
	ds_read2_b32 v[48:49], v56 offset0:66 offset1:74
	ds_read2_b32 v[50:51], v56 offset0:99 offset1:107
	ds_read2_b32 v[52:53], v56 offset0:132 offset1:140
	s_waitcnt lgkmcnt(4)
; __device__ __forceinline__ unsigned pk2(float lo, float hi) { return f2bf(lo) | (f2bf(hi) << 16); }
; #define LAS __attribute__((address_space(3)))
; #define LDS_WAIT() asm volatile("s_waitcnt lgkmcnt(0)" ::: "memory")
;     ...
;     const int c = lane & 7;
; #pragma unroll
;     for (int j = 0; j < 4; ++j) { const int n = (lane >> 3) + 8 * j; const LAS float* s = scr + (8 * c) * 33 + n;
;         u32x4 o; o.x = pk2(s[0 * 33], s[1 * 33]); o.y = pk2(s[2 * 33], s[3 * 33]); o.z = pk2(s[4 * 33], s[5 * 33]); o.w = pk2(s[6 * 33], s[7 * 33]);
;         int rowd = r0 + n;
;         if (qkperm && n0 < 1280) rowd = (n0 & ~255) + 128 * ((n0 >> 5) & 1) + 32 * ((n0 >> 6) & 3) + qk_pos(n);
;         else if (qkperm && n0 >= 2048) { const int gcol = n0 - 2048 + n, half = gcol >> 10, c = gcol & 1023; rowd = 2048 + ((c >> 7) << 8) + 128 * half + (c & 127); }
;         *(u32x4*)(WT + (size_t)rowd * ldo + k0 + 8 * c) = o; }
;     LDS_WAIT(); asm volatile("" ::: "memory");
	v_bfe_u32 v0, v42, 16, 1
	v_add3_u32 v0, v42, v0, s17
	s_waitcnt lgkmcnt(3)
	v_bfe_u32 v37, v46, 16, 1
	v_lshrrev_b32_e32 v0, 16, v0
	v_add3_u32 v37, v46, v37, s17
	ds_read2_b32 v[72:73], v56 offset0:165 offset1:173
	v_and_or_b32 v38, v37, s19, v0
	s_waitcnt lgkmcnt(3)
	v_bfe_u32 v0, v48, 16, 1
	v_add3_u32 v0, v48, v0, s17
	s_waitcnt lgkmcnt(2)
	v_bfe_u32 v37, v50, 16, 1
	ds_read2_b32 v[74:75], v56 offset0:198 offset1:206
	v_lshrrev_b32_e32 v0, 16, v0
	v_add3_u32 v37, v50, v37, s17
	ds_read2_b32 v[76:77], v56 offset0:231 offset1:239
	v_and_or_b32 v39, v37, s19, v0
	s_waitcnt lgkmcnt(3)
	v_bfe_u32 v0, v52, 16, 1
	v_add3_u32 v0, v52, v0, s17
	s_waitcnt lgkmcnt(2)
	v_bfe_u32 v37, v72, 16, 1
	v_lshrrev_b32_e32 v0, 16, v0
	v_add3_u32 v37, v72, v37, s17
	s_lshl_b32 s0, s12, 1
	v_and_or_b32 v40, v37, s19, v0
	s_waitcnt lgkmcnt(1)
	v_bfe_u32 v0, v74, 16, 1
	s_add_i32 s0, s0, 0x1ea00
	s_lshl_b32 s2, s12, 5
	v_add3_u32 v0, v74, v0, s17
	s_waitcnt lgkmcnt(0)
	v_bfe_u32 v37, v76, 16, 1
	s_and_b32 s0, s0, 0x1ffc0
	s_and_b32 s2, s2, 0x3e0
	v_lshrrev_b32_e32 v0, 16, v0
	v_add3_u32 v37, v76, v37, s17
	s_lshl_b32 s0, s0, 1
	v_and_or_b32 v41, v37, s19, v0
	v_or_b32_e32 v0, s2, v55
	v_lshl_add_u64 v[44:45], v[6:7], 0, s[0:1]
	v_lshlrev_b32_e32 v0, 11, v0
	v_lshl_add_u64 v[78:79], v[44:45], 0, v[0:1]
	v_bfe_u32 v0, v43, 16, 1
	v_add3_u32 v0, v43, v0, s17
	v_bfe_u32 v37, v47, 16, 1
	v_lshrrev_b32_e32 v0, 16, v0
	v_add3_u32 v37, v47, v37, s17
	global_store_dwordx4 v[78:79], v[38:41], off
	ds_read2_b32 v[42:43], v56 offset0:16 offset1:24
	s_nop 0
	v_and_or_b32 v38, v37, s19, v0
	v_bfe_u32 v0, v49, 16, 1
	v_add3_u32 v0, v49, v0, s17
	v_bfe_u32 v37, v51, 16, 1
	v_lshrrev_b32_e32 v0, 16, v0
	v_add3_u32 v37, v51, v37, s17
	v_and_or_b32 v39, v37, s19, v0
	v_bfe_u32 v0, v53, 16, 1
	v_add3_u32 v0, v53, v0, s17
	v_bfe_u32 v37, v73, 16, 1
	v_lshrrev_b32_e32 v0, 16, v0
	v_add3_u32 v37, v73, v37, s17
	v_and_or_b32 v40, v37, s19, v0
	v_bfe_u32 v0, v75, 16, 1
	v_add3_u32 v0, v75, v0, s17
	v_bfe_u32 v37, v77, 16, 1
	v_lshrrev_b32_e32 v0, 16, v0
	v_add3_u32 v37, v77, v37, s17
	v_and_or_b32 v41, v37, s19, v0
	v_or_b32_e32 v0, s2, v57
	v_lshlrev_b32_e32 v0, 11, v0
	v_lshl_add_u64 v[46:47], v[44:45], 0, v[0:1]
	global_store_dwordx4 v[46:47], v[38:41], off
	ds_read2_b32 v[46:47], v56 offset0:49 offset1:57
	ds_read2_b32 v[48:49], v56 offset0:82 offset1:90
	ds_read2_b32 v[50:51], v56 offset0:115 offset1:123
	s_waitcnt lgkmcnt(3)
	v_bfe_u32 v0, v42, 16, 1
	v_add3_u32 v0, v42, v0, s17
	s_waitcnt lgkmcnt(2)
	v_bfe_u32 v37, v46, 16, 1
	ds_read2_b32 v[52:53], v56 offset0:148 offset1:156
	v_lshrrev_b32_e32 v0, 16, v0
	v_add3_u32 v37, v46, v37, s17
	ds_read2_b32 v[72:73], v56 offset0:181 offset1:189
	v_and_or_b32 v38, v37, s19, v0
	s_waitcnt lgkmcnt(3)
	v_bfe_u32 v0, v48, 16, 1
	v_add3_u32 v0, v48, v0, s17
	s_waitcnt lgkmcnt(2)
	v_bfe_u32 v37, v50, 16, 1
	ds_read2_b32 v[74:75], v56 offset0:214 offset1:222
	v_lshrrev_b32_e32 v0, 16, v0
	v_add3_u32 v37, v50, v37, s17
	ds_read2_b32 v[76:77], v56 offset0:247 offset1:255
	v_and_or_b32 v39, v37, s19, v0
	s_waitcnt lgkmcnt(3)
	v_bfe_u32 v0, v52, 16, 1
	v_add3_u32 v0, v52, v0, s17
	s_waitcnt lgkmcnt(2)
	v_bfe_u32 v37, v72, 16, 1
	v_lshrrev_b32_e32 v0, 16, v0
	v_add3_u32 v37, v72, v37, s17
	v_and_or_b32 v40, v37, s19, v0
	s_waitcnt lgkmcnt(1)
	v_bfe_u32 v0, v74, 16, 1
	v_add3_u32 v0, v74, v0, s17
	s_waitcnt lgkmcnt(0)
	v_bfe_u32 v37, v76, 16, 1
	v_lshrrev_b32_e32 v0, 16, v0
	v_add3_u32 v37, v76, v37, s17
	v_and_or_b32 v41, v37, s19, v0
	v_or_b32_e32 v0, s2, v58
	v_lshlrev_b32_e32 v0, 11, v0
	v_lshl_add_u64 v[78:79], v[44:45], 0, v[0:1]
	global_store_dwordx4 v[78:79], v[38:41], off
	v_bfe_u32 v37, v47, 16, 1
	v_add3_u32 v37, v47, v37, s17
	v_bfe_u32 v38, v43, 16, 1
	v_add3_u32 v38, v43, v38, s17
	v_lshrrev_b32_e32 v38, 16, v38
	v_bfe_u32 v39, v49, 16, 1
	v_and_or_b32 v38, v37, s19, v38
	v_bfe_u32 v37, v51, 16, 1
	v_add3_u32 v39, v49, v39, s17
	v_add3_u32 v37, v51, v37, s17
	v_lshrrev_b32_e32 v39, 16, v39
	v_bfe_u32 v40, v53, 16, 1
	v_and_or_b32 v39, v37, s19, v39
	v_bfe_u32 v37, v73, 16, 1
	v_add3_u32 v40, v53, v40, s17
	v_add3_u32 v37, v73, v37, s17
	v_lshrrev_b32_e32 v40, 16, v40
	v_bfe_u32 v41, v75, 16, 1
	v_or_b32_e32 v0, s2, v59
	v_and_or_b32 v40, v37, s19, v40
	v_bfe_u32 v37, v77, 16, 1
	v_add3_u32 v41, v75, v41, s17
	v_add3_u32 v37, v77, v37, s17
	v_lshrrev_b32_e32 v41, 16, v41
	v_lshlrev_b32_e32 v0, 11, v0
	v_and_or_b32 v41, v37, s19, v41
	v_lshl_add_u64 v[42:43], v[44:45], 0, v[0:1]
	global_store_dwordx4 v[42:43], v[38:41], off
	s_waitcnt lgkmcnt(0)

; __device__ __forceinline__ unsigned pk2(float lo, float hi) { return f2bf(lo) | (f2bf(hi) << 16); }
; #define LAS __attribute__((address_space(3)))
; #define LDS_WAIT() asm volatile("s_waitcnt lgkmcnt(0)" ::: "memory")
;     ...
; #pragma unroll 8
;     for (int i = 0; i < 32; ++i) { const int kk = 2 * i + (lane >> 5); scr[kk * 33 + (lane & 31)] = __builtin_nontemporal_load(W + (size_t)(k0 + kk) * N + n0 + (lane & 31)); }
;     LDS_WAIT(); asm volatile("" ::: "memory");
;     int r0 = n0;
;     if (upmode) r0 = n0 < FF ? ((n0 >> 7) << 8) + (n0 & 127) : (((n0 - FF) >> 7) << 8) + 128 + ((n0 - FF) & 127);
;     const int c = lane & 7;
; #pragma unroll
;     for (int j = 0; j < 4; ++j) { const int n = (lane >> 3) + 8 * j; const LAS float* s = scr + (8 * c) * 33 + n;
;         u32x4 o; o.x = pk2(s[0 * 33], s[1 * 33]); o.y = pk2(s[2 * 33], s[3 * 33]); o.z = pk2(s[4 * 33], s[5 * 33]); o.w = pk2(s[6 * 33], s[7 * 33]);
.LBB9_59:
	v_lshl_add_u64 v[72:73], v[52:53], 0, s[2:3]
	v_lshl_add_u64 v[74:75], v[50:51], 0, s[2:3]
	v_lshl_add_u64 v[76:77], v[48:49], 0, s[2:3]
	v_lshl_add_u64 v[78:79], v[46:47], 0, s[2:3]
	v_lshl_add_u64 v[80:81], v[44:45], 0, s[2:3]
	v_lshl_add_u64 v[82:83], v[42:43], 0, s[2:3]
	v_lshl_add_u64 v[84:85], v[40:41], 0, s[2:3]
	v_lshl_add_u64 v[86:87], v[38:39], 0, s[2:3]
	global_load_dword v88, v[72:73], off nt
	global_load_dword v89, v[74:75], off nt
	global_load_dword v90, v[76:77], off nt
	global_load_dword v91, v[78:79], off nt
	global_load_dword v92, v[80:81], off nt
	global_load_dword v93, v[82:83], off nt
	global_load_dword v94, v[84:85], off nt
	global_load_dword v95, v[86:87], off nt
	s_add_u32 s2, s2, 0x10000
	s_addc_u32 s3, s3, 0
	v_lshl_add_u64 v[72:73], v[52:53], 0, s[2:3]
	v_lshl_add_u64 v[74:75], v[50:51], 0, s[2:3]
	v_lshl_add_u64 v[76:77], v[48:49], 0, s[2:3]
	v_lshl_add_u64 v[78:79], v[46:47], 0, s[2:3]
	v_lshl_add_u64 v[80:81], v[44:45], 0, s[2:3]
	v_lshl_add_u64 v[82:83], v[42:43], 0, s[2:3]
	v_lshl_add_u64 v[84:85], v[40:41], 0, s[2:3]
	v_lshl_add_u64 v[86:87], v[38:39], 0, s[2:3]
	global_load_dword v96, v[72:73], off nt
	global_load_dword v97, v[74:75], off nt
	global_load_dword v98, v[76:77], off nt
	global_load_dword v99, v[78:79], off nt
	global_load_dword v100, v[80:81], off nt
	global_load_dword v101, v[82:83], off nt
	global_load_dword v102, v[84:85], off nt
	global_load_dword v103, v[86:87], off nt
	s_add_u32 s2, s2, 0x10000
	s_addc_u32 s3, s3, 0
	v_lshl_add_u64 v[72:73], v[52:53], 0, s[2:3]
	v_lshl_add_u64 v[74:75], v[50:51], 0, s[2:3]
	v_lshl_add_u64 v[76:77], v[48:49], 0, s[2:3]
	v_lshl_add_u64 v[78:79], v[46:47], 0, s[2:3]
	v_lshl_add_u64 v[80:81], v[44:45], 0, s[2:3]
	v_lshl_add_u64 v[82:83], v[42:43], 0, s[2:3]
	v_lshl_add_u64 v[84:85], v[40:41], 0, s[2:3]
	v_lshl_add_u64 v[86:87], v[38:39], 0, s[2:3]
	global_load_dword v104, v[72:73], off nt
	global_load_dword v105, v[74:75], off nt
	global_load_dword v106, v[76:77], off nt
	global_load_dword v107, v[78:79], off nt
	global_load_dword v108, v[80:81], off nt
	global_load_dword v109, v[82:83], off nt
	global_load_dword v110, v[84:85], off nt
	global_load_dword v111, v[86:87], off nt
	s_add_u32 s2, s2, 0x10000
	s_addc_u32 s3, s3, 0
	v_lshl_add_u64 v[72:73], v[52:53], 0, s[2:3]
	v_lshl_add_u64 v[74:75], v[50:51], 0, s[2:3]
	v_lshl_add_u64 v[76:77], v[48:49], 0, s[2:3]
	v_lshl_add_u64 v[78:79], v[46:47], 0, s[2:3]
	v_lshl_add_u64 v[80:81], v[44:45], 0, s[2:3]
	v_lshl_add_u64 v[82:83], v[42:43], 0, s[2:3]
	v_lshl_add_u64 v[84:85], v[40:41], 0, s[2:3]
	v_lshl_add_u64 v[86:87], v[38:39], 0, s[2:3]
	global_load_dword v112, v[72:73], off nt
	global_load_dword v113, v[74:75], off nt
	global_load_dword v114, v[76:77], off nt
	global_load_dword v115, v[78:79], off nt
	global_load_dword v116, v[80:81], off nt
	global_load_dword v117, v[82:83], off nt
	global_load_dword v118, v[84:85], off nt
	global_load_dword v119, v[86:87], off nt
	s_add_u32 s2, s2, 0x10000
	s_addc_u32 s3, s3, 0
	v_add_u32_e32 v79, 0x400, v0
	s_waitcnt vmcnt(30)
	ds_write2_b32 v0, v88, v89 offset1:66
	s_waitcnt vmcnt(28)
	ds_write2_b32 v0, v90, v91 offset0:132 offset1:198
	s_waitcnt vmcnt(26)
	ds_write2_b32 v79, v92, v93 offset0:8 offset1:74
	s_waitcnt vmcnt(24)
	ds_write2_b32 v79, v94, v95 offset0:140 offset1:206
	v_add_u32_e32 v0, 0x840, v0
	v_add_u32_e32 v79, 0x400, v0
	s_waitcnt vmcnt(22)
	ds_write2_b32 v0, v96, v97 offset1:66
	s_waitcnt vmcnt(20)
	ds_write2_b32 v0, v98, v99 offset0:132 offset1:198
	s_waitcnt vmcnt(18)
	ds_write2_b32 v79, v100, v101 offset0:8 offset1:74
	s_waitcnt vmcnt(16)
	ds_write2_b32 v79, v102, v103 offset0:140 offset1:206
	v_add_u32_e32 v0, 0x840, v0
	v_add_u32_e32 v79, 0x400, v0
	s_waitcnt vmcnt(14)
	ds_write2_b32 v0, v104, v105 offset1:66
	s_waitcnt vmcnt(12)
	ds_write2_b32 v0, v106, v107 offset0:132 offset1:198
	s_waitcnt vmcnt(10)
	ds_write2_b32 v79, v108, v109 offset0:8 offset1:74
	s_waitcnt vmcnt(8)
	ds_write2_b32 v79, v110, v111 offset0:140 offset1:206
	v_add_u32_e32 v0, 0x840, v0
	v_add_u32_e32 v79, 0x400, v0
	s_waitcnt vmcnt(6)
	ds_write2_b32 v0, v112, v113 offset1:66
	s_waitcnt vmcnt(4)
	ds_write2_b32 v0, v114, v115 offset0:132 offset1:198
	s_waitcnt vmcnt(2)
	ds_write2_b32 v79, v116, v117 offset0:8 offset1:74
	s_waitcnt vmcnt(0)
	ds_write2_b32 v79, v118, v119 offset0:140 offset1:206
	v_add_u32_e32 v0, 0x840, v0
	s_waitcnt lgkmcnt(0)
	ds_read2_b32 v[42:43], v56 offset1:8
	ds_read2_b32 v[46:47], v56 offset0:33 offset1:41
	ds_read2_b32 v[48:49], v56 offset0:66 offset1:74
	ds_read2_b32 v[50:51], v56 offset0:99 offset1:107
	ds_read2_b32 v[52:53], v56 offset0:132 offset1:140
	s_waitcnt lgkmcnt(4)
; __device__ __forceinline__ unsigned pk2(float lo, float hi) { return f2bf(lo) | (f2bf(hi) << 16); }
; #define LAS __attribute__((address_space(3)))
; #define LDS_WAIT() asm volatile("s_waitcnt lgkmcnt(0)" ::: "memory")
;     ...
;     const int c = lane & 7;
; #pragma unroll
;     for (int j = 0; j < 4; ++j) { const int n = (lane >> 3) + 8 * j; const LAS float* s = scr + (8 * c) * 33 + n;
;         u32x4 o; o.x = pk2(s[0 * 33], s[1 * 33]); o.y = pk2(s[2 * 33], s[3 * 33]); o.z = pk2(s[4 * 33], s[5 * 33]); o.w = pk2(s[6 * 33], s[7 * 33]);
;         int rowd = r0 + n;
;         if (qkperm && n0 < 1280) rowd = (n0 & ~255) + 128 * ((n0 >> 5) & 1) + 32 * ((n0 >> 6) & 3) + qk_pos(n);
;         else if (qkperm && n0 >= 2048) { const int gcol = n0 - 2048 + n, half = gcol >> 10, c = gcol & 1023; rowd = 2048 + ((c >> 7) << 8) + 128 * half + (c & 127); }
;         *(u32x4*)(WT + (size_t)rowd * ldo + k0 + 8 * c) = o; }
;     LDS_WAIT(); asm volatile("" ::: "memory");
	v_bfe_u32 v0, v42, 16, 1
	v_add3_u32 v0, v42, v0, s17
	s_waitcnt lgkmcnt(3)
	v_bfe_u32 v37, v46, 16, 1
	v_lshrrev_b32_e32 v0, 16, v0
	v_add3_u32 v37, v46, v37, s17
	ds_read2_b32 v[72:73], v56 offset0:165 offset1:173
	v_and_or_b32 v38, v37, s19, v0
	s_waitcnt lgkmcnt(3)
	v_bfe_u32 v0, v48, 16, 1
	v_add3_u32 v0, v48, v0, s17
	s_waitcnt lgkmcnt(2)
	v_bfe_u32 v37, v50, 16, 1
	ds_read2_b32 v[74:75], v56 offset0:198 offset1:206
	v_lshrrev_b32_e32 v0, 16, v0
	v_add3_u32 v37, v50, v37, s17
	ds_read2_b32 v[76:77], v56 offset0:231 offset1:239
	v_and_or_b32 v39, v37, s19, v0
	s_waitcnt lgkmcnt(3)
	v_bfe_u32 v0, v52, 16, 1
	v_add3_u32 v0, v52, v0, s17
	s_waitcnt lgkmcnt(2)
	v_bfe_u32 v37, v72, 16, 1
	v_lshrrev_b32_e32 v0, 16, v0
	v_add3_u32 v37, v72, v37, s17
	v_and_or_b32 v40, v37, s19, v0
	s_waitcnt lgkmcnt(1)
	v_bfe_u32 v0, v74, 16, 1
	s_lshl_b32 s0, s12, 5
	v_add3_u32 v0, v74, v0, s17
	s_waitcnt lgkmcnt(0)
	v_bfe_u32 v37, v76, 16, 1
	s_and_b32 s2, s0, 0x3e0
	s_lshl_b32 s0, s12, 2
	v_lshrrev_b32_e32 v0, 16, v0
	v_add3_u32 v37, v76, v37, s17
	s_and_b32 s0, s0, 0x380
	v_and_or_b32 v41, v37, s19, v0
	v_or_b32_e32 v0, s2, v55
	v_lshl_add_u64 v[44:45], v[8:9], 0, s[0:1]
	v_lshlrev_b32_e32 v0, 11, v0
	v_lshl_add_u64 v[78:79], v[44:45], 0, v[0:1]
	v_bfe_u32 v0, v43, 16, 1
	v_add3_u32 v0, v43, v0, s17
	v_bfe_u32 v37, v47, 16, 1
	v_lshrrev_b32_e32 v0, 16, v0
	v_add3_u32 v37, v47, v37, s17
	global_store_dwordx4 v[78:79], v[38:41], off
	ds_read2_b32 v[42:43], v56 offset0:16 offset1:24
	s_nop 0
	v_and_or_b32 v38, v37, s19, v0
	v_bfe_u32 v0, v49, 16, 1
	v_add3_u32 v0, v49, v0, s17
	v_bfe_u32 v37, v51, 16, 1
	v_lshrrev_b32_e32 v0, 16, v0
	v_add3_u32 v37, v51, v37, s17
	v_and_or_b32 v39, v37, s19, v0
	v_bfe_u32 v0, v53, 16, 1
	v_add3_u32 v0, v53, v0, s17
	v_bfe_u32 v37, v73, 16, 1
	v_lshrrev_b32_e32 v0, 16, v0
	v_add3_u32 v37, v73, v37, s17
	v_and_or_b32 v40, v37, s19, v0
	v_bfe_u32 v0, v75, 16, 1
	v_add3_u32 v0, v75, v0, s17
	v_bfe_u32 v37, v77, 16, 1
	v_lshrrev_b32_e32 v0, 16, v0
	v_add3_u32 v37, v77, v37, s17
	v_and_or_b32 v41, v37, s19, v0
	v_or_b32_e32 v0, s2, v57
	v_lshlrev_b32_e32 v0, 11, v0
	v_lshl_add_u64 v[46:47], v[44:45], 0, v[0:1]
	global_store_dwordx4 v[46:47], v[38:41], off
	ds_read2_b32 v[46:47], v56 offset0:49 offset1:57
	ds_read2_b32 v[48:49], v56 offset0:82 offset1:90
	ds_read2_b32 v[50:51], v56 offset0:115 offset1:123
	s_waitcnt lgkmcnt(3)
	v_bfe_u32 v0, v42, 16, 1
	v_add3_u32 v0, v42, v0, s17
	s_waitcnt lgkmcnt(2)
	v_bfe_u32 v37, v46, 16, 1
	ds_read2_b32 v[52:53], v56 offset0:148 offset1:156
	v_lshrrev_b32_e32 v0, 16, v0
	v_add3_u32 v37, v46, v37, s17
	ds_read2_b32 v[72:73], v56 offset0:181 offset1:189
	v_and_or_b32 v38, v37, s19, v0
	s_waitcnt lgkmcnt(3)
	v_bfe_u32 v0, v48, 16, 1
	v_add3_u32 v0, v48, v0, s17
	s_waitcnt lgkmcnt(2)
	v_bfe_u32 v37, v50, 16, 1
	ds_read2_b32 v[74:75], v56 offset0:214 offset1:222
	v_lshrrev_b32_e32 v0, 16, v0
	v_add3_u32 v37, v50, v37, s17
	ds_read2_b32 v[76:77], v56 offset0:247 offset1:255
	v_and_or_b32 v39, v37, s19, v0
	s_waitcnt lgkmcnt(3)
	v_bfe_u32 v0, v52, 16, 1
	v_add3_u32 v0, v52, v0, s17
	s_waitcnt lgkmcnt(2)
	v_bfe_u32 v37, v72, 16, 1
	v_lshrrev_b32_e32 v0, 16, v0
	v_add3_u32 v37, v72, v37, s17
	v_and_or_b32 v40, v37, s19, v0
	s_waitcnt lgkmcnt(1)
	v_bfe_u32 v0, v74, 16, 1
	v_add3_u32 v0, v74, v0, s17
	s_waitcnt lgkmcnt(0)
	v_bfe_u32 v37, v76, 16, 1
	v_lshrrev_b32_e32 v0, 16, v0
	v_add3_u32 v37, v76, v37, s17
	v_and_or_b32 v41, v37, s19, v0
	v_or_b32_e32 v0, s2, v58
	v_lshlrev_b32_e32 v0, 11, v0
	v_lshl_add_u64 v[78:79], v[44:45], 0, v[0:1]
	global_store_dwordx4 v[78:79], v[38:41], off
	v_bfe_u32 v37, v47, 16, 1
	v_add3_u32 v37, v47, v37, s17
	v_bfe_u32 v38, v43, 16, 1
	v_add3_u32 v38, v43, v38, s17
	v_lshrrev_b32_e32 v38, 16, v38
	v_bfe_u32 v39, v49, 16, 1
	v_and_or_b32 v38, v37, s19, v38
	v_bfe_u32 v37, v51, 16, 1
	v_add3_u32 v39, v49, v39, s17
	v_add3_u32 v37, v51, v37, s17
	v_lshrrev_b32_e32 v39, 16, v39
	v_bfe_u32 v40, v53, 16, 1
	v_and_or_b32 v39, v37, s19, v39
	v_bfe_u32 v37, v73, 16, 1
	v_add3_u32 v40, v53, v40, s17
	v_add3_u32 v37, v73, v37, s17
	v_lshrrev_b32_e32 v40, 16, v40
	v_bfe_u32 v41, v75, 16, 1
	v_or_b32_e32 v0, s2, v59
	v_and_or_b32 v40, v37, s19, v40
	v_bfe_u32 v37, v77, 16, 1
	v_add3_u32 v41, v75, v41, s17
	v_add3_u32 v37, v77, v37, s17
	v_lshrrev_b32_e32 v41, 16, v41
	v_lshlrev_b32_e32 v0, 11, v0
	v_and_or_b32 v41, v37, s19, v41
	v_lshl_add_u64 v[42:43], v[44:45], 0, v[0:1]
	global_store_dwordx4 v[42:43], v[38:41], off
	s_waitcnt lgkmcnt(0)

; __device__ __forceinline__ unsigned pk2(float lo, float hi) { return f2bf(lo) | (f2bf(hi) << 16); }
; #define LAS __attribute__((address_space(3)))
; #define LDS_WAIT() asm volatile("s_waitcnt lgkmcnt(0)" ::: "memory")
;     ...
; #pragma unroll 8
;     for (int i = 0; i < 32; ++i) { const int kk = 2 * i + (lane >> 5); scr[kk * 33 + (lane & 31)] = __builtin_nontemporal_load(W + (size_t)(k0 + kk) * N + n0 + (lane & 31)); }
;     LDS_WAIT(); asm volatile("" ::: "memory");
;     int r0 = n0;
;     if (upmode) r0 = n0 < FF ? ((n0 >> 7) << 8) + (n0 & 127) : (((n0 - FF) >> 7) << 8) + 128 + ((n0 - FF) & 127);
;     const int c = lane & 7;
; #pragma unroll
;     for (int j = 0; j < 4; ++j) { const int n = (lane >> 3) + 8 * j; const LAS float* s = scr + (8 * c) * 33 + n;
;         u32x4 o; o.x = pk2(s[0 * 33], s[1 * 33]); o.y = pk2(s[2 * 33], s[3 * 33]); o.z = pk2(s[4 * 33], s[5 * 33]); o.w = pk2(s[6 * 33], s[7 * 33]);
.LBB9_64:
	v_lshl_add_u64 v[72:73], v[52:53], 0, s[2:3]
	v_lshl_add_u64 v[74:75], v[50:51], 0, s[2:3]
	v_lshl_add_u64 v[76:77], v[48:49], 0, s[2:3]
	v_lshl_add_u64 v[78:79], v[46:47], 0, s[2:3]
	v_lshl_add_u64 v[80:81], v[44:45], 0, s[2:3]
	v_lshl_add_u64 v[82:83], v[42:43], 0, s[2:3]
	v_lshl_add_u64 v[84:85], v[40:41], 0, s[2:3]
	v_lshl_add_u64 v[86:87], v[38:39], 0, s[2:3]
	global_load_dword v88, v[72:73], off nt
	global_load_dword v89, v[74:75], off nt
	global_load_dword v90, v[76:77], off nt
	global_load_dword v91, v[78:79], off nt
	global_load_dword v92, v[80:81], off nt
	global_load_dword v93, v[82:83], off nt
	global_load_dword v94, v[84:85], off nt
	global_load_dword v95, v[86:87], off nt
	s_add_u32 s2, s2, 0x10000
	s_addc_u32 s3, s3, 0
	v_lshl_add_u64 v[72:73], v[52:53], 0, s[2:3]
	v_lshl_add_u64 v[74:75], v[50:51], 0, s[2:3]
	v_lshl_add_u64 v[76:77], v[48:49], 0, s[2:3]
	v_lshl_add_u64 v[78:79], v[46:47], 0, s[2:3]
	v_lshl_add_u64 v[80:81], v[44:45], 0, s[2:3]
	v_lshl_add_u64 v[82:83], v[42:43], 0, s[2:3]
	v_lshl_add_u64 v[84:85], v[40:41], 0, s[2:3]
	v_lshl_add_u64 v[86:87], v[38:39], 0, s[2:3]
	global_load_dword v96, v[72:73], off nt
	global_load_dword v97, v[74:75], off nt
	global_load_dword v98, v[76:77], off nt
	global_load_dword v99, v[78:79], off nt
	global_load_dword v100, v[80:81], off nt
	global_load_dword v101, v[82:83], off nt
	global_load_dword v102, v[84:85], off nt
	global_load_dword v103, v[86:87], off nt
	s_add_u32 s2, s2, 0x10000
	s_addc_u32 s3, s3, 0
	v_lshl_add_u64 v[72:73], v[52:53], 0, s[2:3]
	v_lshl_add_u64 v[74:75], v[50:51], 0, s[2:3]
	v_lshl_add_u64 v[76:77], v[48:49], 0, s[2:3]
	v_lshl_add_u64 v[78:79], v[46:47], 0, s[2:3]
	v_lshl_add_u64 v[80:81], v[44:45], 0, s[2:3]
	v_lshl_add_u64 v[82:83], v[42:43], 0, s[2:3]
	v_lshl_add_u64 v[84:85], v[40:41], 0, s[2:3]
	v_lshl_add_u64 v[86:87], v[38:39], 0, s[2:3]
	global_load_dword v104, v[72:73], off nt
	global_load_dword v105, v[74:75], off nt
	global_load_dword v106, v[76:77], off nt
	global_load_dword v107, v[78:79], off nt
	global_load_dword v108, v[80:81], off nt
	global_load_dword v109, v[82:83], off nt
	global_load_dword v110, v[84:85], off nt
	global_load_dword v111, v[86:87], off nt
	s_add_u32 s2, s2, 0x10000
	s_addc_u32 s3, s3, 0
	v_lshl_add_u64 v[72:73], v[52:53], 0, s[2:3]
	v_lshl_add_u64 v[74:75], v[50:51], 0, s[2:3]
	v_lshl_add_u64 v[76:77], v[48:49], 0, s[2:3]
	v_lshl_add_u64 v[78:79], v[46:47], 0, s[2:3]
	v_lshl_add_u64 v[80:81], v[44:45], 0, s[2:3]
	v_lshl_add_u64 v[82:83], v[42:43], 0, s[2:3]
	v_lshl_add_u64 v[84:85], v[40:41], 0, s[2:3]
	v_lshl_add_u64 v[86:87], v[38:39], 0, s[2:3]
	global_load_dword v112, v[72:73], off nt
	global_load_dword v113, v[74:75], off nt
	global_load_dword v114, v[76:77], off nt
	global_load_dword v115, v[78:79], off nt
	global_load_dword v116, v[80:81], off nt
	global_load_dword v117, v[82:83], off nt
	global_load_dword v118, v[84:85], off nt
	global_load_dword v119, v[86:87], off nt
	s_add_u32 s2, s2, 0x10000
	s_addc_u32 s3, s3, 0
	v_add_u32_e32 v79, 0x400, v0
	s_waitcnt vmcnt(30)
	ds_write2_b32 v0, v88, v89 offset1:66
	s_waitcnt vmcnt(28)
	ds_write2_b32 v0, v90, v91 offset0:132 offset1:198
	s_waitcnt vmcnt(26)
	ds_write2_b32 v79, v92, v93 offset0:8 offset1:74
	s_waitcnt vmcnt(24)
	ds_write2_b32 v79, v94, v95 offset0:140 offset1:206
	v_add_u32_e32 v0, 0x840, v0
	v_add_u32_e32 v79, 0x400, v0
	s_waitcnt vmcnt(22)
	ds_write2_b32 v0, v96, v97 offset1:66
	s_waitcnt vmcnt(20)
	ds_write2_b32 v0, v98, v99 offset0:132 offset1:198
	s_waitcnt vmcnt(18)
	ds_write2_b32 v79, v100, v101 offset0:8 offset1:74
	s_waitcnt vmcnt(16)
	ds_write2_b32 v79, v102, v103 offset0:140 offset1:206
	v_add_u32_e32 v0, 0x840, v0
	v_add_u32_e32 v79, 0x400, v0
	s_waitcnt vmcnt(14)
	ds_write2_b32 v0, v104, v105 offset1:66
	s_waitcnt vmcnt(12)
	ds_write2_b32 v0, v106, v107 offset0:132 offset1:198
	s_waitcnt vmcnt(10)
	ds_write2_b32 v79, v108, v109 offset0:8 offset1:74
	s_waitcnt vmcnt(8)
	ds_write2_b32 v79, v110, v111 offset0:140 offset1:206
	v_add_u32_e32 v0, 0x840, v0
	v_add_u32_e32 v79, 0x400, v0
	s_waitcnt vmcnt(6)
	ds_write2_b32 v0, v112, v113 offset1:66
	s_waitcnt vmcnt(4)
	ds_write2_b32 v0, v114, v115 offset0:132 offset1:198
	s_waitcnt vmcnt(2)
	ds_write2_b32 v79, v116, v117 offset0:8 offset1:74
	s_waitcnt vmcnt(0)
	ds_write2_b32 v79, v118, v119 offset0:140 offset1:206
	v_add_u32_e32 v0, 0x840, v0
	s_waitcnt lgkmcnt(0)
	ds_read2_b32 v[42:43], v56 offset1:8
	ds_read2_b32 v[46:47], v56 offset0:33 offset1:41
	ds_read2_b32 v[48:49], v56 offset0:66 offset1:74
	ds_read2_b32 v[50:51], v56 offset0:99 offset1:107
	ds_read2_b32 v[52:53], v56 offset0:132 offset1:140
	s_waitcnt lgkmcnt(4)
; __device__ __forceinline__ unsigned pk2(float lo, float hi) { return f2bf(lo) | (f2bf(hi) << 16); }
; #define LAS __attribute__((address_space(3)))
; #define LDS_WAIT() asm volatile("s_waitcnt lgkmcnt(0)" ::: "memory")
;     ...
;     const int c = lane & 7;
; #pragma unroll
;     for (int j = 0; j < 4; ++j) { const int n = (lane >> 3) + 8 * j; const LAS float* s = scr + (8 * c) * 33 + n;
;         u32x4 o; o.x = pk2(s[0 * 33], s[1 * 33]); o.y = pk2(s[2 * 33], s[3 * 33]); o.z = pk2(s[4 * 33], s[5 * 33]); o.w = pk2(s[6 * 33], s[7 * 33]);
;         int rowd = r0 + n;
;         if (qkperm && n0 < 1280) rowd = (n0 & ~255) + 128 * ((n0 >> 5) & 1) + 32 * ((n0 >> 6) & 3) + qk_pos(n);
;         else if (qkperm && n0 >= 2048) { const int gcol = n0 - 2048 + n, half = gcol >> 10, c = gcol & 1023; rowd = 2048 + ((c >> 7) << 8) + 128 * half + (c & 127); }
;         *(u32x4*)(WT + (size_t)rowd * ldo + k0 + 8 * c) = o; }
;     LDS_WAIT(); asm volatile("" ::: "memory");
	v_bfe_u32 v0, v42, 16, 1
	v_add3_u32 v0, v42, v0, s17
	s_waitcnt lgkmcnt(3)
	v_bfe_u32 v37, v46, 16, 1
	v_lshrrev_b32_e32 v0, 16, v0
	v_add3_u32 v37, v46, v37, s17
	ds_read2_b32 v[72:73], v56 offset0:165 offset1:173
	v_and_or_b32 v38, v37, s19, v0
	s_waitcnt lgkmcnt(3)
	v_bfe_u32 v0, v48, 16, 1
	v_add3_u32 v0, v48, v0, s17
	s_waitcnt lgkmcnt(2)
	v_bfe_u32 v37, v50, 16, 1
	ds_read2_b32 v[74:75], v56 offset0:198 offset1:206
	v_lshrrev_b32_e32 v0, 16, v0
	v_add3_u32 v37, v50, v37, s17
	ds_read2_b32 v[76:77], v56 offset0:231 offset1:239
	v_and_or_b32 v39, v37, s19, v0
	s_waitcnt lgkmcnt(3)
	v_bfe_u32 v0, v52, 16, 1
	v_add3_u32 v0, v52, v0, s17
	s_waitcnt lgkmcnt(2)
	v_bfe_u32 v37, v72, 16, 1
	v_lshrrev_b32_e32 v0, 16, v0
	v_add3_u32 v37, v72, v37, s17
	s_lshl_b32 s0, s12, 1
	v_and_or_b32 v40, v37, s19, v0
	s_waitcnt lgkmcnt(1)
	v_bfe_u32 v0, v74, 16, 1
	s_add_i32 s0, s0, 0x1f000
	s_lshl_b32 s2, s12, 5
	v_add3_u32 v0, v74, v0, s17
	s_waitcnt lgkmcnt(0)
	v_bfe_u32 v37, v76, 16, 1
	s_and_b32 s0, s0, 0x1ffc0
	s_and_b32 s2, s2, 0x3e0
	v_lshrrev_b32_e32 v0, 16, v0
	v_add3_u32 v37, v76, v37, s17
	s_lshl_b32 s0, s0, 1
	v_and_or_b32 v41, v37, s19, v0
	v_or_b32_e32 v0, s2, v55
	v_lshl_add_u64 v[44:45], v[10:11], 0, s[0:1]
	v_lshlrev_b32_e32 v0, 11, v0
	v_lshl_add_u64 v[78:79], v[44:45], 0, v[0:1]
	v_bfe_u32 v0, v43, 16, 1
	v_add3_u32 v0, v43, v0, s17
	v_bfe_u32 v37, v47, 16, 1
	v_lshrrev_b32_e32 v0, 16, v0
	v_add3_u32 v37, v47, v37, s17
	global_store_dwordx4 v[78:79], v[38:41], off
	ds_read2_b32 v[42:43], v56 offset0:16 offset1:24
	s_nop 0
	v_and_or_b32 v38, v37, s19, v0
	v_bfe_u32 v0, v49, 16, 1
	v_add3_u32 v0, v49, v0, s17
	v_bfe_u32 v37, v51, 16, 1
	v_lshrrev_b32_e32 v0, 16, v0
	v_add3_u32 v37, v51, v37, s17
	v_and_or_b32 v39, v37, s19, v0
	v_bfe_u32 v0, v53, 16, 1
	v_add3_u32 v0, v53, v0, s17
	v_bfe_u32 v37, v73, 16, 1
	v_lshrrev_b32_e32 v0, 16, v0
	v_add3_u32 v37, v73, v37, s17
	v_and_or_b32 v40, v37, s19, v0
	v_bfe_u32 v0, v75, 16, 1
	v_add3_u32 v0, v75, v0, s17
	v_bfe_u32 v37, v77, 16, 1
	v_lshrrev_b32_e32 v0, 16, v0
	v_add3_u32 v37, v77, v37, s17
	v_and_or_b32 v41, v37, s19, v0
	v_or_b32_e32 v0, s2, v57
	v_lshlrev_b32_e32 v0, 11, v0
	v_lshl_add_u64 v[46:47], v[44:45], 0, v[0:1]
	global_store_dwordx4 v[46:47], v[38:41], off
	ds_read2_b32 v[46:47], v56 offset0:49 offset1:57
	ds_read2_b32 v[48:49], v56 offset0:82 offset1:90
	ds_read2_b32 v[50:51], v56 offset0:115 offset1:123
	s_waitcnt lgkmcnt(3)
	v_bfe_u32 v0, v42, 16, 1
	v_add3_u32 v0, v42, v0, s17
	s_waitcnt lgkmcnt(2)
	v_bfe_u32 v37, v46, 16, 1
	ds_read2_b32 v[52:53], v56 offset0:148 offset1:156
	v_lshrrev_b32_e32 v0, 16, v0
	v_add3_u32 v37, v46, v37, s17
	ds_read2_b32 v[72:73], v56 offset0:181 offset1:189
	v_and_or_b32 v38, v37, s19, v0
	s_waitcnt lgkmcnt(3)
	v_bfe_u32 v0, v48, 16, 1
	v_add3_u32 v0, v48, v0, s17
	s_waitcnt lgkmcnt(2)
	v_bfe_u32 v37, v50, 16, 1
	ds_read2_b32 v[74:75], v56 offset0:214 offset1:222
	v_lshrrev_b32_e32 v0, 16, v0
	v_add3_u32 v37, v50, v37, s17
	ds_read2_b32 v[76:77], v56 offset0:247 offset1:255
	v_and_or_b32 v39, v37, s19, v0
	s_waitcnt lgkmcnt(3)
	v_bfe_u32 v0, v52, 16, 1
	v_add3_u32 v0, v52, v0, s17
	s_waitcnt lgkmcnt(2)
	v_bfe_u32 v37, v72, 16, 1
	v_lshrrev_b32_e32 v0, 16, v0
	v_add3_u32 v37, v72, v37, s17
	v_and_or_b32 v40, v37, s19, v0
	s_waitcnt lgkmcnt(1)
	v_bfe_u32 v0, v74, 16, 1
	v_add3_u32 v0, v74, v0, s17
	s_waitcnt lgkmcnt(0)
	v_bfe_u32 v37, v76, 16, 1
	v_lshrrev_b32_e32 v0, 16, v0
	v_add3_u32 v37, v76, v37, s17
	v_and_or_b32 v41, v37, s19, v0
	v_or_b32_e32 v0, s2, v58
	v_lshlrev_b32_e32 v0, 11, v0
	v_lshl_add_u64 v[78:79], v[44:45], 0, v[0:1]
	global_store_dwordx4 v[78:79], v[38:41], off
	v_bfe_u32 v37, v47, 16, 1
	v_add3_u32 v37, v47, v37, s17
	v_bfe_u32 v38, v43, 16, 1
	v_add3_u32 v38, v43, v38, s17
	v_lshrrev_b32_e32 v38, 16, v38
	v_bfe_u32 v39, v49, 16, 1
	v_and_or_b32 v38, v37, s19, v38
	v_bfe_u32 v37, v51, 16, 1
	v_add3_u32 v39, v49, v39, s17
	v_add3_u32 v37, v51, v37, s17
	v_lshrrev_b32_e32 v39, 16, v39
	v_bfe_u32 v40, v53, 16, 1
	v_and_or_b32 v39, v37, s19, v39
	v_bfe_u32 v37, v73, 16, 1
	v_add3_u32 v40, v53, v40, s17
	v_add3_u32 v37, v73, v37, s17
	v_lshrrev_b32_e32 v40, 16, v40
	v_bfe_u32 v41, v75, 16, 1
	v_or_b32_e32 v0, s2, v59
	v_and_or_b32 v40, v37, s19, v40
	v_bfe_u32 v37, v77, 16, 1
	v_add3_u32 v41, v75, v41, s17
	v_add3_u32 v37, v77, v37, s17
	v_lshrrev_b32_e32 v41, 16, v41
	v_lshlrev_b32_e32 v0, 11, v0
	v_and_or_b32 v41, v37, s19, v41
	v_lshl_add_u64 v[42:43], v[44:45], 0, v[0:1]
	global_store_dwordx4 v[42:43], v[38:41], off
	s_waitcnt lgkmcnt(0)

; __device__ __forceinline__ unsigned pk2(float lo, float hi) { return f2bf(lo) | (f2bf(hi) << 16); }
; #define LAS __attribute__((address_space(3)))
; #define LDS_WAIT() asm volatile("s_waitcnt lgkmcnt(0)" ::: "memory")
;     ...
; #pragma unroll 8
;     for (int i = 0; i < 32; ++i) { const int kk = 2 * i + (lane >> 5); scr[kk * 33 + (lane & 31)] = __builtin_nontemporal_load(W + (size_t)(k0 + kk) * N + n0 + (lane & 31)); }
;     LDS_WAIT(); asm volatile("" ::: "memory");
;     int r0 = n0;
;     if (upmode) r0 = n0 < FF ? ((n0 >> 7) << 8) + (n0 & 127) : (((n0 - FF) >> 7) << 8) + 128 + ((n0 - FF) & 127);
;     const int c = lane & 7;
; #pragma unroll
;     for (int j = 0; j < 4; ++j) { const int n = (lane >> 3) + 8 * j; const LAS float* s = scr + (8 * c) * 33 + n;
;         u32x4 o; o.x = pk2(s[0 * 33], s[1 * 33]); o.y = pk2(s[2 * 33], s[3 * 33]); o.z = pk2(s[4 * 33], s[5 * 33]); o.w = pk2(s[6 * 33], s[7 * 33]);
.LBB9_69:
	v_lshl_add_u64 v[72:73], v[52:53], 0, s[2:3]
	v_lshl_add_u64 v[74:75], v[50:51], 0, s[2:3]
	v_lshl_add_u64 v[76:77], v[48:49], 0, s[2:3]
	v_lshl_add_u64 v[78:79], v[46:47], 0, s[2:3]
	v_lshl_add_u64 v[80:81], v[44:45], 0, s[2:3]
	v_lshl_add_u64 v[82:83], v[42:43], 0, s[2:3]
	v_lshl_add_u64 v[84:85], v[40:41], 0, s[2:3]
	v_lshl_add_u64 v[86:87], v[38:39], 0, s[2:3]
	global_load_dword v88, v[72:73], off nt
	global_load_dword v89, v[74:75], off nt
	global_load_dword v90, v[76:77], off nt
	global_load_dword v91, v[78:79], off nt
	global_load_dword v92, v[80:81], off nt
	global_load_dword v93, v[82:83], off nt
	global_load_dword v94, v[84:85], off nt
	global_load_dword v95, v[86:87], off nt
	s_add_u32 s2, s2, 0x40000
	s_addc_u32 s3, s3, 0
	v_lshl_add_u64 v[72:73], v[52:53], 0, s[2:3]
	v_lshl_add_u64 v[74:75], v[50:51], 0, s[2:3]
	v_lshl_add_u64 v[76:77], v[48:49], 0, s[2:3]
	v_lshl_add_u64 v[78:79], v[46:47], 0, s[2:3]
	v_lshl_add_u64 v[80:81], v[44:45], 0, s[2:3]
	v_lshl_add_u64 v[82:83], v[42:43], 0, s[2:3]
	v_lshl_add_u64 v[84:85], v[40:41], 0, s[2:3]
	v_lshl_add_u64 v[86:87], v[38:39], 0, s[2:3]
	global_load_dword v96, v[72:73], off nt
	global_load_dword v97, v[74:75], off nt
	global_load_dword v98, v[76:77], off nt
	global_load_dword v99, v[78:79], off nt
	global_load_dword v100, v[80:81], off nt
	global_load_dword v101, v[82:83], off nt
	global_load_dword v102, v[84:85], off nt
	global_load_dword v103, v[86:87], off nt
	s_add_u32 s2, s2, 0x40000
	s_addc_u32 s3, s3, 0
	v_lshl_add_u64 v[72:73], v[52:53], 0, s[2:3]
	v_lshl_add_u64 v[74:75], v[50:51], 0, s[2:3]
	v_lshl_add_u64 v[76:77], v[48:49], 0, s[2:3]
	v_lshl_add_u64 v[78:79], v[46:47], 0, s[2:3]
	v_lshl_add_u64 v[80:81], v[44:45], 0, s[2:3]
	v_lshl_add_u64 v[82:83], v[42:43], 0, s[2:3]
	v_lshl_add_u64 v[84:85], v[40:41], 0, s[2:3]
	v_lshl_add_u64 v[86:87], v[38:39], 0, s[2:3]
	global_load_dword v104, v[72:73], off nt
	global_load_dword v105, v[74:75], off nt
	global_load_dword v106, v[76:77], off nt
	global_load_dword v107, v[78:79], off nt
	global_load_dword v108, v[80:81], off nt
	global_load_dword v109, v[82:83], off nt
	global_load_dword v110, v[84:85], off nt
	global_load_dword v111, v[86:87], off nt
	s_add_u32 s2, s2, 0x40000
	s_addc_u32 s3, s3, 0
	v_lshl_add_u64 v[72:73], v[52:53], 0, s[2:3]
	v_lshl_add_u64 v[74:75], v[50:51], 0, s[2:3]
	v_lshl_add_u64 v[76:77], v[48:49], 0, s[2:3]
	v_lshl_add_u64 v[78:79], v[46:47], 0, s[2:3]
	v_lshl_add_u64 v[80:81], v[44:45], 0, s[2:3]
	v_lshl_add_u64 v[82:83], v[42:43], 0, s[2:3]
	v_lshl_add_u64 v[84:85], v[40:41], 0, s[2:3]
	v_lshl_add_u64 v[86:87], v[38:39], 0, s[2:3]
	global_load_dword v112, v[72:73], off nt
	global_load_dword v113, v[74:75], off nt
	global_load_dword v114, v[76:77], off nt
	global_load_dword v115, v[78:79], off nt
	global_load_dword v116, v[80:81], off nt
	global_load_dword v117, v[82:83], off nt
	global_load_dword v118, v[84:85], off nt
	global_load_dword v119, v[86:87], off nt
	s_add_u32 s2, s2, 0x40000
	s_addc_u32 s3, s3, 0
	v_add_u32_e32 v79, 0x400, v0
	s_waitcnt vmcnt(30)
	ds_write2_b32 v0, v88, v89 offset1:66
	s_waitcnt vmcnt(28)
	ds_write2_b32 v0, v90, v91 offset0:132 offset1:198
	s_waitcnt vmcnt(26)
	ds_write2_b32 v79, v92, v93 offset0:8 offset1:74
	s_waitcnt vmcnt(24)
	ds_write2_b32 v79, v94, v95 offset0:140 offset1:206
	v_add_u32_e32 v0, 0x840, v0
	v_add_u32_e32 v79, 0x400, v0
	s_waitcnt vmcnt(22)
	ds_write2_b32 v0, v96, v97 offset1:66
	s_waitcnt vmcnt(20)
	ds_write2_b32 v0, v98, v99 offset0:132 offset1:198
	s_waitcnt vmcnt(18)
	ds_write2_b32 v79, v100, v101 offset0:8 offset1:74
	s_waitcnt vmcnt(16)
	ds_write2_b32 v79, v102, v103 offset0:140 offset1:206
	v_add_u32_e32 v0, 0x840, v0
	v_add_u32_e32 v79, 0x400, v0
	s_waitcnt vmcnt(14)
	ds_write2_b32 v0, v104, v105 offset1:66
	s_waitcnt vmcnt(12)
	ds_write2_b32 v0, v106, v107 offset0:132 offset1:198
	s_waitcnt vmcnt(10)
	ds_write2_b32 v79, v108, v109 offset0:8 offset1:74
	s_waitcnt vmcnt(8)
	ds_write2_b32 v79, v110, v111 offset0:140 offset1:206
	v_add_u32_e32 v0, 0x840, v0
	v_add_u32_e32 v79, 0x400, v0
	s_waitcnt vmcnt(6)
	ds_write2_b32 v0, v112, v113 offset1:66
	s_waitcnt vmcnt(4)
	ds_write2_b32 v0, v114, v115 offset0:132 offset1:198
	s_waitcnt vmcnt(2)
	ds_write2_b32 v79, v116, v117 offset0:8 offset1:74
	s_waitcnt vmcnt(0)
	ds_write2_b32 v79, v118, v119 offset0:140 offset1:206
	v_add_u32_e32 v0, 0x840, v0
	s_waitcnt lgkmcnt(0)
	ds_read2_b32 v[44:45], v56 offset1:8
	ds_read2_b32 v[46:47], v56 offset0:33 offset1:41
	ds_read2_b32 v[48:49], v56 offset0:66 offset1:74
	ds_read2_b32 v[50:51], v56 offset0:99 offset1:107
	ds_read2_b32 v[52:53], v56 offset0:132 offset1:140
	s_waitcnt lgkmcnt(4)
	v_bfe_u32 v37, v44, 16, 1
	v_add3_u32 v37, v44, v37, s17
	s_waitcnt lgkmcnt(3)
	v_bfe_u32 v38, v46, 16, 1
	s_lshl_b32 s2, s0, 6
	s_and_b32 s3, s8, 0x60
	v_lshrrev_b32_e32 v37, 16, v37
	v_add3_u32 v38, v46, v38, s17
	ds_read2_b32 v[72:73], v56 offset0:165 offset1:173
	s_cmp_lt_i32 s0, 40
	v_and_or_b32 v38, v38, s19, v37
	s_waitcnt lgkmcnt(3)
; __device__ __forceinline__ unsigned pk2(float lo, float hi) { return f2bf(lo) | (f2bf(hi) << 16); }
; #define LAS __attribute__((address_space(3)))
; #define LDS_WAIT() asm volatile("s_waitcnt lgkmcnt(0)" ::: "memory")
;     ...
;     for (int j = 0; j < 4; ++j) { const int n = (lane >> 3) + 8 * j; const LAS float* s = scr + (8 * c) * 33 + n;
;         u32x4 o; o.x = pk2(s[0 * 33], s[1 * 33]); o.y = pk2(s[2 * 33], s[3 * 33]); o.z = pk2(s[4 * 33], s[5 * 33]); o.w = pk2(s[6 * 33], s[7 * 33]);
;         int rowd = r0 + n;
;         if (qkperm && n0 < 1280) rowd = (n0 & ~255) + 128 * ((n0 >> 5) & 1) + 32 * ((n0 >> 6) & 3) + qk_pos(n);
;         else if (qkperm && n0 >= 2048) { const int gcol = n0 - 2048 + n, half = gcol >> 10, c = gcol & 1023; rowd = 2048 + ((c >> 7) << 8) + 128 * half + (c & 127); }
;         *(u32x4*)(WT + (size_t)rowd * ldo + k0 + 8 * c) = o; }
;     LDS_WAIT(); asm volatile("" ::: "memory");
	v_bfe_u32 v37, v48, 16, 1
	s_cselect_b64 vcc, -1, 0
	s_add_i32 s9, s8, 0xfffff800
	v_add3_u32 v37, v48, v37, s17
	s_waitcnt lgkmcnt(2)
	v_bfe_u32 v39, v50, 16, 1
	ds_read2_b32 v[74:75], v56 offset0:198 offset1:206
	s_and_b32 s2, s2, 0x700
	s_ashr_i32 s9, s9, 3
	v_lshrrev_b32_e32 v37, 16, v37
	v_add3_u32 v39, v50, v39, s17
	ds_read2_b32 v[76:77], v56 offset0:231 offset1:239
	s_and_b32 s9, s9, 0xffffff80
	s_or_b32 s2, s3, s2
	v_and_or_b32 v39, v39, s19, v37
	s_waitcnt lgkmcnt(3)
	v_bfe_u32 v37, v52, 16, 1
	s_ashr_i32 s11, s10, 31
	s_add_i32 s2, s9, s2
	s_lshl_b32 s9, s0, 7
	v_add3_u32 v37, v52, v37, s17
	s_waitcnt lgkmcnt(2)
	v_bfe_u32 v40, v72, 16, 1
	v_lshl_add_u64 v[42:43], s[10:11], 1, v[12:13]
	s_and_b32 s9, s9, 0x80
	s_lshl_b32 s10, s0, 4
	v_lshrrev_b32_e32 v37, 16, v37
	v_add3_u32 v40, v72, v40, s17
	s_addk_i32 s2, 0x800
	s_and_b32 s3, s8, 0xffffff00
	s_and_b32 s10, s10, 0x60
	v_or_b32_e32 v0, s9, v60
	v_and_or_b32 v40, v40, s19, v37
	s_waitcnt lgkmcnt(1)
	v_bfe_u32 v37, v74, 16, 1
	s_cmp_gt_i32 s0, 63
	v_or_b32_e32 v0, s3, v0
	v_add3_u32 v37, v74, v37, s17
	s_waitcnt lgkmcnt(0)
	v_bfe_u32 v41, v76, 16, 1
	v_or_b32_e32 v0, s10, v0
	v_lshrrev_b32_e32 v37, 16, v37
	v_add3_u32 v41, v76, v41, s17
	s_cselect_b32 s0, s2, s8
	v_and_or_b32 v41, v41, s19, v37
	v_or_b32_e32 v37, v0, v61
	v_or_b32_e32 v44, s0, v55
	v_cndmask_b32_e32 v78, v44, v37, vcc
	v_ashrrev_i32_e32 v79, 31, v78
	v_lshlrev_b64 v[78:79], 11, v[78:79]
	v_lshl_add_u64 v[78:79], v[42:43], 0, v[78:79]
	global_store_dwordx4 v[78:79], v[38:41], off
	v_bfe_u32 v44, v77, 16, 1
	v_add3_u32 v44, v77, v44, s17
	v_bfe_u32 v38, v45, 16, 1
	v_add3_u32 v38, v45, v38, s17
	v_bfe_u32 v39, v47, 16, 1
	v_lshrrev_b32_e32 v38, 16, v38
	v_add3_u32 v39, v47, v39, s17
	v_and_or_b32 v38, v39, s19, v38
	v_bfe_u32 v39, v49, 16, 1
	v_add3_u32 v39, v49, v39, s17
	v_bfe_u32 v40, v51, 16, 1
	v_lshrrev_b32_e32 v39, 16, v39
	v_add3_u32 v40, v51, v40, s17
	v_and_or_b32 v39, v40, s19, v39
	v_bfe_u32 v40, v53, 16, 1
	v_add3_u32 v40, v53, v40, s17
	v_bfe_u32 v41, v73, 16, 1
	v_lshrrev_b32_e32 v40, 16, v40
	v_add3_u32 v41, v73, v41, s17
	v_and_or_b32 v40, v41, s19, v40
	v_bfe_u32 v41, v75, 16, 1
	v_add3_u32 v41, v75, v41, s17
	v_lshrrev_b32_e32 v41, 16, v41
	v_and_or_b32 v41, v44, s19, v41
	v_or_b32_e32 v44, v0, v62
	v_or_b32_e32 v45, s0, v57
	v_cndmask_b32_e32 v44, v45, v44, vcc
	v_ashrrev_i32_e32 v45, 31, v44
	v_lshlrev_b64 v[44:45], 11, v[44:45]
	ds_read2_b32 v[46:47], v56 offset0:16 offset1:24
	v_lshl_add_u64 v[44:45], v[42:43], 0, v[44:45]
	global_store_dwordx4 v[44:45], v[38:41], off
	ds_read2_b32 v[44:45], v56 offset0:49 offset1:57
	ds_read2_b32 v[48:49], v56 offset0:82 offset1:90
	ds_read2_b32 v[50:51], v56 offset0:115 offset1:123
	s_waitcnt lgkmcnt(3)
	v_bfe_u32 v38, v46, 16, 1
	v_add3_u32 v38, v46, v38, s17
	s_waitcnt lgkmcnt(2)
	v_bfe_u32 v39, v44, 16, 1
	ds_read2_b32 v[52:53], v56 offset0:148 offset1:156
	v_lshrrev_b32_e32 v38, 16, v38
	v_add3_u32 v39, v44, v39, s17
	ds_read2_b32 v[72:73], v56 offset0:181 offset1:189
	v_and_or_b32 v38, v39, s19, v38
	s_waitcnt lgkmcnt(3)
	v_bfe_u32 v39, v48, 16, 1
	v_add3_u32 v39, v48, v39, s17
	s_waitcnt lgkmcnt(2)
	v_bfe_u32 v40, v50, 16, 1
	ds_read2_b32 v[74:75], v56 offset0:214 offset1:222
	v_lshrrev_b32_e32 v39, 16, v39
	v_add3_u32 v40, v50, v40, s17
	ds_read2_b32 v[76:77], v56 offset0:247 offset1:255
	v_and_or_b32 v39, v40, s19, v39
	s_waitcnt lgkmcnt(3)
	v_bfe_u32 v40, v52, 16, 1
	v_add3_u32 v40, v52, v40, s17
	s_waitcnt lgkmcnt(2)
	v_bfe_u32 v41, v72, 16, 1
	v_lshrrev_b32_e32 v40, 16, v40
	v_add3_u32 v41, v72, v41, s17
	v_and_or_b32 v40, v41, s19, v40
	s_waitcnt lgkmcnt(1)
	v_bfe_u32 v41, v74, 16, 1
	v_add3_u32 v41, v74, v41, s17
	s_waitcnt lgkmcnt(0)
	v_bfe_u32 v44, v76, 16, 1
	v_lshrrev_b32_e32 v41, 16, v41
	v_add3_u32 v44, v76, v44, s17
	v_and_or_b32 v41, v44, s19, v41
	v_or_b32_e32 v37, 4, v37
	v_or_b32_e32 v44, s0, v58
	v_cndmask_b32_e32 v78, v44, v37, vcc
	v_or_b32_e32 v0, v0, v63
	v_or_b32_e32 v37, s0, v59
	v_ashrrev_i32_e32 v79, 31, v78
	v_cndmask_b32_e32 v44, v37, v0, vcc
	v_bfe_u32 v37, v47, 16, 1
	v_lshlrev_b64 v[78:79], 11, v[78:79]
	v_bfe_u32 v0, v45, 16, 1
	v_add3_u32 v37, v47, v37, s17
	v_lshl_add_u64 v[78:79], v[42:43], 0, v[78:79]
	v_add3_u32 v0, v45, v0, s17
	v_lshrrev_b32_e32 v37, 16, v37
	global_store_dwordx4 v[78:79], v[38:41], off
	v_ashrrev_i32_e32 v45, 31, v44
	v_lshlrev_b64 v[44:45], 11, v[44:45]
	v_and_or_b32 v38, v0, s19, v37
	v_bfe_u32 v37, v49, 16, 1
	v_bfe_u32 v0, v51, 16, 1
	v_add3_u32 v37, v49, v37, s17
	v_add3_u32 v0, v51, v0, s17
	v_lshrrev_b32_e32 v37, 16, v37
	v_and_or_b32 v39, v0, s19, v37
	v_bfe_u32 v37, v53, 16, 1
	v_bfe_u32 v0, v73, 16, 1
	v_add3_u32 v37, v53, v37, s17
	v_add3_u32 v0, v73, v0, s17
	v_lshrrev_b32_e32 v37, 16, v37
	v_and_or_b32 v40, v0, s19, v37
	v_bfe_u32 v37, v75, 16, 1
	v_bfe_u32 v0, v77, 16, 1
	v_add3_u32 v37, v75, v37, s17
	v_add3_u32 v0, v77, v0, s17
	v_lshrrev_b32_e32 v37, 16, v37
	v_and_or_b32 v41, v0, s19, v37
	v_lshl_add_u64 v[42:43], v[42:43], 0, v[44:45]
	global_store_dwordx4 v[42:43], v[38:41], off
	s_waitcnt lgkmcnt(0)
	s_branch .LBB9_32
